# attention loops unrolled by LDS buffer parity: static LDS offsets, no per-block parity arithmetic, fewer waits
# speedup vs baseline: 1.0084x; 1.0057x over previous
; #define LAS __attribute__((address_space(3)))
; template <int MODE  > ...
;     ...
;         const bool has_next = rem != 0ull; int jn = 0;
;         if (has_next) { jn = 63 - __builtin_clzll(rem); rem &= ~(1ull << jn);
;             kreg = *(const u32x4*)(Kg + (size_t)(64 * jn + skey) * 128 + schunk * 8);
;             if (NEEDV) vreg = *(const u32x4*)(Vg + (size_t)(64 * jn + skey) * 128 + schunk * 8); }
;         const bool selbit = (MODE == 1) ? (((selmask >> j) & 1ull) != 0ull) : true;
;         bool active = true;
;         if (MODE == 1) active = __builtin_amdgcn_ballot_w64(selbit) != 0ull;
;         if (active) {
;             const LAS bf16_t* kb = (const LAS bf16_t*)(lds + A_KBUF) + cur * 64 * KPITCH;
;             constexpr int STEP = CMPM ? 16 : 1;
;             const int Bint = CMPM ? (1024 * j + 31 - t + 64 * h) : (64 * j - t + 4 * h);
;             const float sl = slope2 * (float)STEP;
;             const float mref = st.m; const bool fresh = !(mref > -1e28f);
;             const float mest = fresh ? 0.f : mref;
;             const float basef = selbit ? (slope2 * (float)Bint - mest) : -1e30f;
;             int ptype;
;             if (MODE == 1) ptype = (j == cblk) ? 1 : 0;
;             else if (MODE == 2) ptype = (j == cblk) ? 1 : ((j == cblk - 8) ? 2 : 0);
;             else ptype = (64 * j + 63 <= 4 * cblk - 2) ? 0 : 1;
;             f32x16 s0, s1;
;             { const float sl2 = sl + sl, sl3 = sl2 + sl;
; #pragma unroll
;               for (int g8 = 0; g8 < 4; ++g8) {
;                   const float b0 = __builtin_fmaf(sl, (float)(8 * g8), basef), b1 = __builtin_fmaf(sl, (float)(8 * g8 + 32), basef);
;                   s0[4 * g8] = b0; s0[4 * g8 + 1] = b0 + sl; s0[4 * g8 + 2] = b0 + sl2; s0[4 * g8 + 3] = b0 + sl3;
;                   s1[4 * g8] = b1; s1[4 * g8 + 1] = b1 + sl; s1[4 * g8 + 2] = b1 + sl2; s1[4 * g8 + 3] = b1 + sl3;
;               } }
;             if (ptype == 1) {
;                 const float thr = 0.5f * slope2 - mest;
; #pragma unroll
;                 for (int i = 0; i < 16; ++i) { s0[i] = (s0[i] < thr) ? s0[i] : -1e30f; s1[i] = (s1[i] < thr) ? s1[i] : -1e30f; }
.LBB0_146:
	s_mov_b32 s21, 0
	s_cmp_eq_u64 s[22:23], 0
	s_cbranch_scc1 .Lm00_noload
	s_flbit_i32_b64 s91, s[22:23]
	s_xor_b32 s91, s91, 63
	s_lshl_b64 vcc, 1, s91
	s_andn2_b64 s[22:23], s[22:23], vcc
	s_mov_b32 s21, 1
	v_lshl_add_u32 v2, s91, 6, v211
	v_ashrrev_i32_e32 v3, 31, v2
	v_lshlrev_b64 v[2:3], 8, v[2:3]
	v_lshl_add_u64 v[4:5], v[192:193], 0, v[2:3]
	v_lshl_add_u64 v[2:3], v[194:195], 0, v[2:3]
	global_load_dwordx4 v[160:163], v[4:5], off
	global_load_dwordx4 v[164:167], v[2:3], off
.Lm00_noload:
.Lm0_body0:
	ds_read_b128 v[80:83], v216
	ds_read_b128 v[84:87], v216 offset:4608
	ds_read_b128 v[88:91], v216 offset:32
	ds_read_b128 v[92:95], v216 offset:4640
	ds_read_b128 v[96:99], v216 offset:64
	ds_read_b128 v[100:103], v216 offset:4672
	ds_read_b128 v[104:107], v216 offset:96
	ds_read_b128 v[108:111], v216 offset:4704
	v_lshl_add_u32 v1, s90, 10, v217
	v_cvt_f32_i32_e32 v48, v1
	v_cmp_nlt_f32_e64 s[14:15], s71, v219
	s_lshl_b32 s17, s90, 6
	s_or_b32 s17, s17, 63
	s_cmp_le_i32 s17, s69
	v_cndmask_b32_e64 v1, v219, 0, s[14:15]
	v_fma_f32 v60, v186, v48, -v1
	v_fma_f32 v64, 0, v190, v60
	v_fmamk_f32 v68, v190, 0x41000000, v60
	v_fmamk_f32 v72, v190, 0x41800000, v60
	v_fmamk_f32 v76, v190, 0x41c00000, v60
	v_fmamk_f32 v48, v190, 0x42000000, v60
	v_fmamk_f32 v52, v190, 0x42200000, v60
	v_fmamk_f32 v56, v190, 0x42400000, v60
	v_fmac_f32_e32 v60, 0x42600000, v190
	v_add_f32_e32 v65, v190, v64
	v_add_f32_e32 v66, v191, v64
	v_add_f32_e32 v67, v187, v64
	v_add_f32_e32 v69, v190, v68
	v_add_f32_e32 v70, v191, v68
	v_add_f32_e32 v71, v187, v68
	v_add_f32_e32 v73, v190, v72
	v_add_f32_e32 v74, v191, v72
	v_add_f32_e32 v75, v187, v72
	v_add_f32_e32 v77, v190, v76
	v_add_f32_e32 v78, v191, v76
	v_add_f32_e32 v79, v187, v76
	v_add_f32_e32 v49, v190, v48
	v_add_f32_e32 v50, v191, v48
	v_add_f32_e32 v51, v187, v48
	v_add_f32_e32 v53, v190, v52
	v_add_f32_e32 v54, v191, v52
	v_add_f32_e32 v55, v187, v52
	v_add_f32_e32 v57, v190, v56
	v_add_f32_e32 v58, v191, v56
	v_add_f32_e32 v59, v187, v56
	v_add_f32_e32 v61, v190, v60
	v_add_f32_e32 v62, v191, v60
	v_add_f32_e32 v63, v187, v60
	s_cbranch_scc1 .Lm00_qk
	v_sub_f32_e32 v253, v189, v1
	v_cmp_lt_f32_e32 vcc, v64, v253
	s_nop 1
	v_cndmask_b32_e32 v64, v241, v64, vcc
	v_cmp_lt_f32_e32 vcc, v65, v253
	s_nop 1
	v_cndmask_b32_e32 v65, v241, v65, vcc
	v_cmp_lt_f32_e32 vcc, v66, v253
	s_nop 1
	v_cndmask_b32_e32 v66, v241, v66, vcc
	v_cmp_lt_f32_e32 vcc, v67, v253
	s_nop 1
	v_cndmask_b32_e32 v67, v241, v67, vcc
	v_cmp_lt_f32_e32 vcc, v68, v253
	s_nop 1
	v_cndmask_b32_e32 v68, v241, v68, vcc
	v_cmp_lt_f32_e32 vcc, v69, v253
	s_nop 1
	v_cndmask_b32_e32 v69, v241, v69, vcc
	v_cmp_lt_f32_e32 vcc, v70, v253
	s_nop 1
	v_cndmask_b32_e32 v70, v241, v70, vcc
	v_cmp_lt_f32_e32 vcc, v71, v253
	s_nop 1
	v_cndmask_b32_e32 v71, v241, v71, vcc
	v_cmp_lt_f32_e32 vcc, v72, v253
	s_nop 1
	v_cndmask_b32_e32 v72, v241, v72, vcc
	v_cmp_lt_f32_e32 vcc, v73, v253
	s_nop 1
	v_cndmask_b32_e32 v73, v241, v73, vcc
	v_cmp_lt_f32_e32 vcc, v74, v253
	s_nop 1
	v_cndmask_b32_e32 v74, v241, v74, vcc
	v_cmp_lt_f32_e32 vcc, v75, v253
	s_nop 1
	v_cndmask_b32_e32 v75, v241, v75, vcc
	v_cmp_lt_f32_e32 vcc, v76, v253
	s_nop 1
	v_cndmask_b32_e32 v76, v241, v76, vcc
	v_cmp_lt_f32_e32 vcc, v77, v253
	s_nop 1
	v_cndmask_b32_e32 v77, v241, v77, vcc
	v_cmp_lt_f32_e32 vcc, v78, v253
	s_nop 1
	v_cndmask_b32_e32 v78, v241, v78, vcc
	v_cmp_lt_f32_e32 vcc, v79, v253
	s_nop 1
	v_cndmask_b32_e32 v79, v241, v79, vcc
	v_cmp_lt_f32_e32 vcc, v48, v253
	s_nop 1
	v_cndmask_b32_e32 v48, v241, v48, vcc
	v_cmp_lt_f32_e32 vcc, v49, v253
	s_nop 1
	v_cndmask_b32_e32 v49, v241, v49, vcc
	v_cmp_lt_f32_e32 vcc, v50, v253
	s_nop 1
	v_cndmask_b32_e32 v50, v241, v50, vcc
	v_cmp_lt_f32_e32 vcc, v51, v253
	s_nop 1
	v_cndmask_b32_e32 v51, v241, v51, vcc
	v_cmp_lt_f32_e32 vcc, v52, v253
	s_nop 1
	v_cndmask_b32_e32 v52, v241, v52, vcc
	v_cmp_lt_f32_e32 vcc, v53, v253
	s_nop 1
	v_cndmask_b32_e32 v53, v241, v53, vcc
	v_cmp_lt_f32_e32 vcc, v54, v253
	s_nop 1
	v_cndmask_b32_e32 v54, v241, v54, vcc
	v_cmp_lt_f32_e32 vcc, v55, v253
	s_nop 1
	v_cndmask_b32_e32 v55, v241, v55, vcc
	v_cmp_lt_f32_e32 vcc, v56, v253
	s_nop 1
	v_cndmask_b32_e32 v56, v241, v56, vcc
	v_cmp_lt_f32_e32 vcc, v57, v253
	s_nop 1
	v_cndmask_b32_e32 v57, v241, v57, vcc
	v_cmp_lt_f32_e32 vcc, v58, v253
	s_nop 1
	v_cndmask_b32_e32 v58, v241, v58, vcc
	v_cmp_lt_f32_e32 vcc, v59, v253
	s_nop 1
	v_cndmask_b32_e32 v59, v241, v59, vcc
	v_cmp_lt_f32_e32 vcc, v60, v253
	s_nop 1
	v_cndmask_b32_e32 v60, v241, v60, vcc
	v_cmp_lt_f32_e32 vcc, v61, v253
	s_nop 1
	v_cndmask_b32_e32 v61, v241, v61, vcc
	v_cmp_lt_f32_e32 vcc, v62, v253
	s_nop 1
	v_cndmask_b32_e32 v62, v241, v62, vcc
	v_cmp_lt_f32_e32 vcc, v63, v253
	s_nop 1
	v_cndmask_b32_e32 v63, v241, v63, vcc
; #define LAS __attribute__((address_space(3)))
; __device__ __forceinline__ float shflx(float v, int mask, int lane) { return __builtin_bit_cast(float, __builtin_amdgcn_ds_bpermute(((lane ^ mask) & 63) << 2, __builtin_bit_cast(int, v))); }
; template <int MODE  > ...
;     ...
;             for (int kk = 0; kk < 4; ++kk) {
;                 const bf16x8 k0 = *(const LAS bf16x8*)(kb + col * KPITCH + kk * 16 + h * 8);
;                 const bf16x8 k1 = *(const LAS bf16x8*)(kb + (32 + col) * KPITCH + kk * 16 + h * 8);
;                 s0 = __builtin_amdgcn_mfma_f32_32x32x16_bf16(k0, qf[kk], s0, 0, 0, 0);
;                 s1 = __builtin_amdgcn_mfma_f32_32x32x16_bf16(k1, qf[kk], s1, 0, 0, 0);
;             }
;             if (MODE != 3) {
;                 float mx = fmaxf(s0[0], s1[0]);
; #pragma unroll
;                 for (int i = 1; i < 16; ++i) mx = fmaxf(mx, fmaxf(s0[i], s1[i]));
;                 mx = fmaxf(mx, shflx(mx, 32, lane));
;                 float alpha = 1.f;
;                 if (__builtin_amdgcn_ballot_w64(fresh || mx > 0.f) != 0ull) {
;                     const float moldr = fresh ? -1e29f : 0.f, mnewr = fmaxf(moldr, mx);
;                     alpha = __builtin_amdgcn_exp2f(moldr - mnewr);
;                     st.m = mest + mnewr;
; #pragma unroll
;                     for (int i = 0; i < 16; ++i) { s0[i] = __builtin_amdgcn_exp2f(s0[i] - mnewr); s1[i] = __builtin_amdgcn_exp2f(s1[i] - mnewr); }
;                     st.o0 *= alpha; st.o1 *= alpha;
.Lm00_qk:
	s_waitcnt lgkmcnt(6)
	v_mfma_f32_32x32x16_bf16 v[64:79], v[80:83], v[144:147], v[64:79]
	v_mfma_f32_32x32x16_bf16 v[48:63], v[84:87], v[144:147], v[48:63]
	s_waitcnt lgkmcnt(4)
	v_mfma_f32_32x32x16_bf16 v[64:79], v[88:91], v[148:151], v[64:79]
	v_mfma_f32_32x32x16_bf16 v[48:63], v[92:95], v[148:151], v[48:63]
	s_waitcnt lgkmcnt(2)
	v_mfma_f32_32x32x16_bf16 v[64:79], v[96:99], v[152:155], v[64:79]
	v_mfma_f32_32x32x16_bf16 v[48:63], v[100:103], v[152:155], v[48:63]
	s_waitcnt lgkmcnt(0)
	v_mfma_f32_32x32x16_bf16 v[64:79], v[104:107], v[156:159], v[64:79]
	v_mfma_f32_32x32x16_bf16 v[48:63], v[108:111], v[156:159], v[48:63]
	ds_read_b64_tr_b16 v[80:81], v218 offset:18432
	ds_read_b64_tr_b16 v[82:83], v218 offset:19968
	ds_read_b64_tr_b16 v[84:85], v218 offset:18496
	ds_read_b64_tr_b16 v[86:87], v218 offset:20032
	ds_read_b64_tr_b16 v[88:89], v218 offset:21504
	ds_read_b64_tr_b16 v[90:91], v218 offset:23040
	ds_read_b64_tr_b16 v[92:93], v218 offset:21568
	ds_read_b64_tr_b16 v[94:95], v218 offset:23104
	s_nop 3
	v_max3_f32 v234, v64, v65, v66
	v_max3_f32 v234, v234, v67, v68
	v_max3_f32 v234, v234, v69, v70
	v_max3_f32 v234, v234, v71, v72
	v_max3_f32 v234, v234, v73, v74
	v_max3_f32 v234, v234, v75, v76
	v_max3_f32 v234, v234, v77, v78
	v_max3_f32 v235, v48, v49, v50
	v_max3_f32 v235, v235, v51, v52
	v_max3_f32 v235, v235, v53, v54
	v_max3_f32 v235, v235, v55, v56
	v_max3_f32 v235, v235, v57, v58
	v_max3_f32 v235, v235, v59, v60
	v_max3_f32 v235, v235, v61, v62
	v_max3_f32 v234, v234, v79, v63
	v_max_f32_e32 v234, v234, v235
	v_mov_b32_e32 v235, v234
	s_waitcnt lgkmcnt(7)
	ds_read_b64_tr_b16 v[96:97], v218 offset:24576
	ds_read_b64_tr_b16 v[98:99], v218 offset:26112
	ds_read_b64_tr_b16 v[100:101], v218 offset:24640
	ds_read_b64_tr_b16 v[102:103], v218 offset:26176
	ds_read_b64_tr_b16 v[104:105], v218 offset:27648
	ds_read_b64_tr_b16 v[106:107], v218 offset:29184
	ds_read_b64_tr_b16 v[108:109], v218 offset:27712
	ds_read_b64_tr_b16 v[110:111], v218 offset:29248
	v_permlane32_swap_b32_e32 v235, v234
	v_max_f32_e32 v234, v234, v235
	v_cmp_lt_f32_e32 vcc, 0, v234
	s_or_b64 vcc, s[14:15], vcc
	s_cbranch_vccz .Lm00_norescale
	v_cndmask_b32_e64 v235, 0, v242, s[14:15]
	v_max_f32_e32 v234, v235, v234
	v_sub_f32_e32 v235, v235, v234
	v_exp_f32_e32 v6, v235
	v_add_f32_e32 v219, v1, v234
	v_sub_f32_e32 v128, v64, v234
	v_exp_f32_e32 v128, v128
	v_sub_f32_e32 v112, v48, v234
	v_exp_f32_e32 v112, v112
	v_sub_f32_e32 v129, v65, v234
	v_exp_f32_e32 v129, v129
	v_sub_f32_e32 v113, v49, v234
	v_exp_f32_e32 v113, v113
	v_sub_f32_e32 v130, v66, v234
	v_exp_f32_e32 v130, v130
	v_sub_f32_e32 v114, v50, v234
	v_exp_f32_e32 v114, v114
	v_sub_f32_e32 v131, v67, v234
	v_exp_f32_e32 v131, v131
	v_sub_f32_e32 v115, v51, v234
	v_exp_f32_e32 v115, v115
	v_sub_f32_e32 v132, v68, v234
	v_exp_f32_e32 v132, v132
	v_sub_f32_e32 v116, v52, v234
	v_exp_f32_e32 v116, v116
	v_sub_f32_e32 v133, v69, v234
	v_exp_f32_e32 v133, v133
	v_sub_f32_e32 v117, v53, v234
	v_exp_f32_e32 v117, v117
	v_sub_f32_e32 v134, v70, v234
	v_exp_f32_e32 v134, v134
	v_sub_f32_e32 v118, v54, v234
	v_exp_f32_e32 v118, v118
	v_sub_f32_e32 v135, v71, v234
	v_exp_f32_e32 v135, v135
	v_sub_f32_e32 v119, v55, v234
	v_exp_f32_e32 v119, v119
	v_sub_f32_e32 v136, v72, v234
	v_exp_f32_e32 v136, v136
	v_sub_f32_e32 v120, v56, v234
	v_exp_f32_e32 v120, v120
	v_sub_f32_e32 v137, v73, v234
	v_exp_f32_e32 v137, v137
	v_sub_f32_e32 v121, v57, v234
	v_exp_f32_e32 v121, v121
	v_sub_f32_e32 v138, v74, v234
	v_exp_f32_e32 v138, v138
	v_sub_f32_e32 v122, v58, v234
	v_exp_f32_e32 v122, v122
	v_sub_f32_e32 v139, v75, v234
	v_exp_f32_e32 v139, v139
	v_sub_f32_e32 v123, v59, v234
	v_exp_f32_e32 v123, v123
	v_sub_f32_e32 v140, v76, v234
	v_exp_f32_e32 v140, v140
	v_sub_f32_e32 v124, v60, v234
	v_exp_f32_e32 v124, v124
	v_sub_f32_e32 v141, v77, v234
	v_exp_f32_e32 v141, v141
	v_sub_f32_e32 v125, v61, v234
	v_exp_f32_e32 v125, v125
	v_sub_f32_e32 v142, v78, v234
	v_exp_f32_e32 v142, v142
	v_sub_f32_e32 v126, v62, v234
	v_exp_f32_e32 v126, v126
	v_sub_f32_e32 v143, v79, v234
	v_exp_f32_e32 v143, v143
	v_sub_f32_e32 v127, v63, v234
	v_exp_f32_e32 v127, v127
	v_pk_mul_f32 v[16:17], v[16:17], v[6:7] op_sel_hi:[1,0]
	v_pk_mul_f32 v[18:19], v[18:19], v[6:7] op_sel_hi:[1,0]
	v_pk_mul_f32 v[20:21], v[20:21], v[6:7] op_sel_hi:[1,0]
	v_pk_mul_f32 v[22:23], v[22:23], v[6:7] op_sel_hi:[1,0]
	v_pk_mul_f32 v[24:25], v[24:25], v[6:7] op_sel_hi:[1,0]
	v_pk_mul_f32 v[26:27], v[26:27], v[6:7] op_sel_hi:[1,0]
	v_pk_mul_f32 v[28:29], v[28:29], v[6:7] op_sel_hi:[1,0]
	v_pk_mul_f32 v[30:31], v[30:31], v[6:7] op_sel_hi:[1,0]
	v_pk_mul_f32 v[32:33], v[32:33], v[6:7] op_sel_hi:[1,0]
	v_pk_mul_f32 v[34:35], v[34:35], v[6:7] op_sel_hi:[1,0]
	v_pk_mul_f32 v[36:37], v[36:37], v[6:7] op_sel_hi:[1,0]
	v_pk_mul_f32 v[38:39], v[38:39], v[6:7] op_sel_hi:[1,0]
	v_pk_mul_f32 v[40:41], v[40:41], v[6:7] op_sel_hi:[1,0]
	v_pk_mul_f32 v[42:43], v[42:43], v[6:7] op_sel_hi:[1,0]
	v_pk_mul_f32 v[44:45], v[44:45], v[6:7] op_sel_hi:[1,0]
	v_pk_mul_f32 v[46:47], v[46:47], v[6:7] op_sel_hi:[1,0]
	s_branch .Lm00_pv

; #define LAS __attribute__((address_space(3)))
; template <int MODE  > ...
;     ...
;         if (has_next) {
;             LAS bf16_t* kb = (LAS bf16_t*)(lds + A_KBUF) + (cur ^ 1) * 64 * KPITCH;
;             *(LAS u32x4*)(kb + skey * KPITCH + schunk * 8) = kreg;
;             if (NEEDV) { LAS bf16_t* vb = (LAS bf16_t*)(lds + A_VBUF) + (cur ^ 1) * 64 * VPITCH;
;                 *(LAS u32x4*)(vb + skey * VPITCH + schunk * 8) = vreg; }
;         }
;         __syncthreads();
.Lm0_stage0:
	s_cmp_eq_u32 s20, 0
	s_cbranch_scc1 .Lm0_bot0
	s_cmp_eq_u32 s21, 0
	s_cbranch_scc1 .Lm00_w0
	s_waitcnt vmcnt(2)
	s_branch .Lm00_w1

; #define LAS __attribute__((address_space(3)))
; template <int MODE  > ...
;     ...
;         const bool has_next = rem != 0ull; int jn = 0;
;         if (has_next) { jn = 63 - __builtin_clzll(rem); rem &= ~(1ull << jn);
;             kreg = *(const u32x4*)(Kg + (size_t)(64 * jn + skey) * 128 + schunk * 8);
;             if (NEEDV) vreg = *(const u32x4*)(Vg + (size_t)(64 * jn + skey) * 128 + schunk * 8); }
;         const bool selbit = (MODE == 1) ? (((selmask >> j) & 1ull) != 0ull) : true;
;         bool active = true;
;         if (MODE == 1) active = __builtin_amdgcn_ballot_w64(selbit) != 0ull;
;         if (active) {
;             const LAS bf16_t* kb = (const LAS bf16_t*)(lds + A_KBUF) + cur * 64 * KPITCH;
;             constexpr int STEP = CMPM ? 16 : 1;
;             const int Bint = CMPM ? (1024 * j + 31 - t + 64 * h) : (64 * j - t + 4 * h);
;             const float sl = slope2 * (float)STEP;
;             const float mref = st.m; const bool fresh = !(mref > -1e28f);
;             const float mest = fresh ? 0.f : mref;
;             const float basef = selbit ? (slope2 * (float)Bint - mest) : -1e30f;
;             int ptype;
;             if (MODE == 1) ptype = (j == cblk) ? 1 : 0;
;             else if (MODE == 2) ptype = (j == cblk) ? 1 : ((j == cblk - 8) ? 2 : 0);
;             else ptype = (64 * j + 63 <= 4 * cblk - 2) ? 0 : 1;
;             f32x16 s0, s1;
;             { const float sl2 = sl + sl, sl3 = sl2 + sl;
; #pragma unroll
;               for (int g8 = 0; g8 < 4; ++g8) {
;                   const float b0 = __builtin_fmaf(sl, (float)(8 * g8), basef), b1 = __builtin_fmaf(sl, (float)(8 * g8 + 32), basef);
;                   s0[4 * g8] = b0; s0[4 * g8 + 1] = b0 + sl; s0[4 * g8 + 2] = b0 + sl2; s0[4 * g8 + 3] = b0 + sl3;
;                   s1[4 * g8] = b1; s1[4 * g8 + 1] = b1 + sl; s1[4 * g8 + 2] = b1 + sl2; s1[4 * g8 + 3] = b1 + sl3;
;               } }
;             if (ptype == 1) {
;     ...
;         if (has_next) {
;             LAS bf16_t* kb = (LAS bf16_t*)(lds + A_KBUF) + (cur ^ 1) * 64 * KPITCH;
;             *(LAS u32x4*)(kb + skey * KPITCH + schunk * 8) = kreg;
;             if (NEEDV) { LAS bf16_t* vb = (LAS bf16_t*)(lds + A_VBUF) + (cur ^ 1) * 64 * VPITCH;
;                 *(LAS u32x4*)(vb + skey * VPITCH + schunk * 8) = vreg; }
;         }
;         __syncthreads();
;         if (!has_next) break;
;         j = jn; cur ^= 1;
;     }
.Lm00_w1:
	ds_write_b128 v214, v[226:229] offset:9216
	ds_write_b128 v215, v[230:233] offset:30720
.Lm0_bot0:
	s_waitcnt lgkmcnt(0)
	s_barrier
	s_cmp_eq_u32 s20, 0
	s_cbranch_scc1 .Lm0_exit
	s_mov_b32 s90, s89
	s_mov_b32 s89, s91
	s_mov_b32 s20, s21
.Lm0_loop1:
	s_mov_b32 s21, 0
	s_cmp_eq_u64 s[22:23], 0
	s_cbranch_scc1 .Lm01_noload
	s_flbit_i32_b64 s91, s[22:23]
	s_xor_b32 s91, s91, 63
	s_lshl_b64 vcc, 1, s91
	s_andn2_b64 s[22:23], s[22:23], vcc
	s_mov_b32 s21, 1
	v_lshl_add_u32 v2, s91, 6, v211
	v_ashrrev_i32_e32 v3, 31, v2
	v_lshlrev_b64 v[2:3], 8, v[2:3]
	v_lshl_add_u64 v[4:5], v[192:193], 0, v[2:3]
	v_lshl_add_u64 v[2:3], v[194:195], 0, v[2:3]
	global_load_dwordx4 v[226:229], v[4:5], off
	global_load_dwordx4 v[230:233], v[2:3], off
.Lm01_noload:
.Lm0_body1:
	ds_read_b128 v[80:83], v216 offset:9216
	ds_read_b128 v[84:87], v216 offset:13824
	ds_read_b128 v[88:91], v216 offset:9248
	ds_read_b128 v[92:95], v216 offset:13856
	ds_read_b128 v[96:99], v216 offset:9280
	ds_read_b128 v[100:103], v216 offset:13888
	ds_read_b128 v[104:107], v216 offset:9312
	ds_read_b128 v[108:111], v216 offset:13920
	v_lshl_add_u32 v1, s90, 10, v217
	v_cvt_f32_i32_e32 v48, v1
	v_cmp_nlt_f32_e64 s[14:15], s71, v219
	s_lshl_b32 s17, s90, 6
	s_or_b32 s17, s17, 63
	s_cmp_le_i32 s17, s69
	v_cndmask_b32_e64 v1, v219, 0, s[14:15]
	v_fma_f32 v60, v186, v48, -v1
	v_fma_f32 v64, 0, v190, v60
	v_fmamk_f32 v68, v190, 0x41000000, v60
	v_fmamk_f32 v72, v190, 0x41800000, v60
	v_fmamk_f32 v76, v190, 0x41c00000, v60
	v_fmamk_f32 v48, v190, 0x42000000, v60
	v_fmamk_f32 v52, v190, 0x42200000, v60
	v_fmamk_f32 v56, v190, 0x42400000, v60
	v_fmac_f32_e32 v60, 0x42600000, v190
	v_add_f32_e32 v65, v190, v64
	v_add_f32_e32 v66, v191, v64
	v_add_f32_e32 v67, v187, v64
	v_add_f32_e32 v69, v190, v68
	v_add_f32_e32 v70, v191, v68
	v_add_f32_e32 v71, v187, v68
	v_add_f32_e32 v73, v190, v72
	v_add_f32_e32 v74, v191, v72
	v_add_f32_e32 v75, v187, v72
	v_add_f32_e32 v77, v190, v76
	v_add_f32_e32 v78, v191, v76
	v_add_f32_e32 v79, v187, v76
	v_add_f32_e32 v49, v190, v48
	v_add_f32_e32 v50, v191, v48
	v_add_f32_e32 v51, v187, v48
	v_add_f32_e32 v53, v190, v52
	v_add_f32_e32 v54, v191, v52
	v_add_f32_e32 v55, v187, v52
	v_add_f32_e32 v57, v190, v56
	v_add_f32_e32 v58, v191, v56
	v_add_f32_e32 v59, v187, v56
	v_add_f32_e32 v61, v190, v60
	v_add_f32_e32 v62, v191, v60
	v_add_f32_e32 v63, v187, v60
	s_cbranch_scc1 .Lm01_qk
	v_sub_f32_e32 v253, v189, v1
	v_cmp_lt_f32_e32 vcc, v64, v253
	s_nop 1
	v_cndmask_b32_e32 v64, v241, v64, vcc
	v_cmp_lt_f32_e32 vcc, v65, v253
	s_nop 1
	v_cndmask_b32_e32 v65, v241, v65, vcc
	v_cmp_lt_f32_e32 vcc, v66, v253
	s_nop 1
	v_cndmask_b32_e32 v66, v241, v66, vcc
	v_cmp_lt_f32_e32 vcc, v67, v253
	s_nop 1
	v_cndmask_b32_e32 v67, v241, v67, vcc
	v_cmp_lt_f32_e32 vcc, v68, v253
	s_nop 1
	v_cndmask_b32_e32 v68, v241, v68, vcc
	v_cmp_lt_f32_e32 vcc, v69, v253
	s_nop 1
	v_cndmask_b32_e32 v69, v241, v69, vcc
	v_cmp_lt_f32_e32 vcc, v70, v253
	s_nop 1
	v_cndmask_b32_e32 v70, v241, v70, vcc
	v_cmp_lt_f32_e32 vcc, v71, v253
	s_nop 1
	v_cndmask_b32_e32 v71, v241, v71, vcc
	v_cmp_lt_f32_e32 vcc, v72, v253
	s_nop 1
	v_cndmask_b32_e32 v72, v241, v72, vcc
	v_cmp_lt_f32_e32 vcc, v73, v253
	s_nop 1
	v_cndmask_b32_e32 v73, v241, v73, vcc
	v_cmp_lt_f32_e32 vcc, v74, v253
	s_nop 1
	v_cndmask_b32_e32 v74, v241, v74, vcc
	v_cmp_lt_f32_e32 vcc, v75, v253
	s_nop 1
	v_cndmask_b32_e32 v75, v241, v75, vcc
	v_cmp_lt_f32_e32 vcc, v76, v253
	s_nop 1
	v_cndmask_b32_e32 v76, v241, v76, vcc
	v_cmp_lt_f32_e32 vcc, v77, v253
	s_nop 1
	v_cndmask_b32_e32 v77, v241, v77, vcc
	v_cmp_lt_f32_e32 vcc, v78, v253
	s_nop 1
	v_cndmask_b32_e32 v78, v241, v78, vcc
	v_cmp_lt_f32_e32 vcc, v79, v253
	s_nop 1
	v_cndmask_b32_e32 v79, v241, v79, vcc
	v_cmp_lt_f32_e32 vcc, v48, v253
	s_nop 1
	v_cndmask_b32_e32 v48, v241, v48, vcc
	v_cmp_lt_f32_e32 vcc, v49, v253
	s_nop 1
	v_cndmask_b32_e32 v49, v241, v49, vcc
	v_cmp_lt_f32_e32 vcc, v50, v253
	s_nop 1
	v_cndmask_b32_e32 v50, v241, v50, vcc
	v_cmp_lt_f32_e32 vcc, v51, v253
	s_nop 1
	v_cndmask_b32_e32 v51, v241, v51, vcc
	v_cmp_lt_f32_e32 vcc, v52, v253
	s_nop 1
	v_cndmask_b32_e32 v52, v241, v52, vcc
	v_cmp_lt_f32_e32 vcc, v53, v253
	s_nop 1
	v_cndmask_b32_e32 v53, v241, v53, vcc
	v_cmp_lt_f32_e32 vcc, v54, v253
	s_nop 1
	v_cndmask_b32_e32 v54, v241, v54, vcc
	v_cmp_lt_f32_e32 vcc, v55, v253
	s_nop 1
	v_cndmask_b32_e32 v55, v241, v55, vcc
	v_cmp_lt_f32_e32 vcc, v56, v253
	s_nop 1
	v_cndmask_b32_e32 v56, v241, v56, vcc
	v_cmp_lt_f32_e32 vcc, v57, v253
	s_nop 1
	v_cndmask_b32_e32 v57, v241, v57, vcc
	v_cmp_lt_f32_e32 vcc, v58, v253
	s_nop 1
	v_cndmask_b32_e32 v58, v241, v58, vcc
	v_cmp_lt_f32_e32 vcc, v59, v253
	s_nop 1
	v_cndmask_b32_e32 v59, v241, v59, vcc
	v_cmp_lt_f32_e32 vcc, v60, v253
	s_nop 1
	v_cndmask_b32_e32 v60, v241, v60, vcc
	v_cmp_lt_f32_e32 vcc, v61, v253
	s_nop 1
	v_cndmask_b32_e32 v61, v241, v61, vcc
	v_cmp_lt_f32_e32 vcc, v62, v253
	s_nop 1
	v_cndmask_b32_e32 v62, v241, v62, vcc
	v_cmp_lt_f32_e32 vcc, v63, v253
	s_nop 1
	v_cndmask_b32_e32 v63, v241, v63, vcc
; #define LAS __attribute__((address_space(3)))
; __device__ __forceinline__ float shflx(float v, int mask, int lane) { return __builtin_bit_cast(float, __builtin_amdgcn_ds_bpermute(((lane ^ mask) & 63) << 2, __builtin_bit_cast(int, v))); }
; template <int MODE  > ...
;     ...
;             for (int kk = 0; kk < 4; ++kk) {
;                 const bf16x8 k0 = *(const LAS bf16x8*)(kb + col * KPITCH + kk * 16 + h * 8);
;                 const bf16x8 k1 = *(const LAS bf16x8*)(kb + (32 + col) * KPITCH + kk * 16 + h * 8);
;                 s0 = __builtin_amdgcn_mfma_f32_32x32x16_bf16(k0, qf[kk], s0, 0, 0, 0);
;                 s1 = __builtin_amdgcn_mfma_f32_32x32x16_bf16(k1, qf[kk], s1, 0, 0, 0);
;             }
;             if (MODE != 3) {
;                 float mx = fmaxf(s0[0], s1[0]);
; #pragma unroll
;                 for (int i = 1; i < 16; ++i) mx = fmaxf(mx, fmaxf(s0[i], s1[i]));
;                 mx = fmaxf(mx, shflx(mx, 32, lane));
;                 float alpha = 1.f;
;                 if (__builtin_amdgcn_ballot_w64(fresh || mx > 0.f) != 0ull) {
;                     const float moldr = fresh ? -1e29f : 0.f, mnewr = fmaxf(moldr, mx);
;                     alpha = __builtin_amdgcn_exp2f(moldr - mnewr);
;                     st.m = mest + mnewr;
; #pragma unroll
;                     for (int i = 0; i < 16; ++i) { s0[i] = __builtin_amdgcn_exp2f(s0[i] - mnewr); s1[i] = __builtin_amdgcn_exp2f(s1[i] - mnewr); }
;                     st.o0 *= alpha; st.o1 *= alpha;
.Lm01_qk:
	s_waitcnt lgkmcnt(6)
	v_mfma_f32_32x32x16_bf16 v[64:79], v[80:83], v[144:147], v[64:79]
	v_mfma_f32_32x32x16_bf16 v[48:63], v[84:87], v[144:147], v[48:63]
	s_waitcnt lgkmcnt(4)
	v_mfma_f32_32x32x16_bf16 v[64:79], v[88:91], v[148:151], v[64:79]
	v_mfma_f32_32x32x16_bf16 v[48:63], v[92:95], v[148:151], v[48:63]
	s_waitcnt lgkmcnt(2)
	v_mfma_f32_32x32x16_bf16 v[64:79], v[96:99], v[152:155], v[64:79]
	v_mfma_f32_32x32x16_bf16 v[48:63], v[100:103], v[152:155], v[48:63]
	s_waitcnt lgkmcnt(0)
	v_mfma_f32_32x32x16_bf16 v[64:79], v[104:107], v[156:159], v[64:79]
	v_mfma_f32_32x32x16_bf16 v[48:63], v[108:111], v[156:159], v[48:63]
	ds_read_b64_tr_b16 v[80:81], v218 offset:30720
	ds_read_b64_tr_b16 v[82:83], v218 offset:32256
	ds_read_b64_tr_b16 v[84:85], v218 offset:30784
	ds_read_b64_tr_b16 v[86:87], v218 offset:32320
	ds_read_b64_tr_b16 v[88:89], v218 offset:33792
	ds_read_b64_tr_b16 v[90:91], v218 offset:35328
	ds_read_b64_tr_b16 v[92:93], v218 offset:33856
	ds_read_b64_tr_b16 v[94:95], v218 offset:35392
	s_nop 3
	v_max3_f32 v234, v64, v65, v66
	v_max3_f32 v234, v234, v67, v68
	v_max3_f32 v234, v234, v69, v70
	v_max3_f32 v234, v234, v71, v72
	v_max3_f32 v234, v234, v73, v74
	v_max3_f32 v234, v234, v75, v76
	v_max3_f32 v234, v234, v77, v78
	v_max3_f32 v235, v48, v49, v50
	v_max3_f32 v235, v235, v51, v52
	v_max3_f32 v235, v235, v53, v54
	v_max3_f32 v235, v235, v55, v56
	v_max3_f32 v235, v235, v57, v58
	v_max3_f32 v235, v235, v59, v60
	v_max3_f32 v235, v235, v61, v62
	v_max3_f32 v234, v234, v79, v63
	v_max_f32_e32 v234, v234, v235
	v_mov_b32_e32 v235, v234
	s_waitcnt lgkmcnt(7)
	ds_read_b64_tr_b16 v[96:97], v218 offset:36864
	ds_read_b64_tr_b16 v[98:99], v218 offset:38400
	ds_read_b64_tr_b16 v[100:101], v218 offset:36928
	ds_read_b64_tr_b16 v[102:103], v218 offset:38464
	ds_read_b64_tr_b16 v[104:105], v218 offset:39936
	ds_read_b64_tr_b16 v[106:107], v218 offset:41472
	ds_read_b64_tr_b16 v[108:109], v218 offset:40000
	ds_read_b64_tr_b16 v[110:111], v218 offset:41536
	v_permlane32_swap_b32_e32 v235, v234
	v_max_f32_e32 v234, v234, v235
	v_cmp_lt_f32_e32 vcc, 0, v234
	s_or_b64 vcc, s[14:15], vcc
	s_cbranch_vccz .Lm01_norescale
	v_cndmask_b32_e64 v235, 0, v242, s[14:15]
	v_max_f32_e32 v234, v235, v234
	v_sub_f32_e32 v235, v235, v234
	v_exp_f32_e32 v6, v235
	v_add_f32_e32 v219, v1, v234
	v_sub_f32_e32 v128, v64, v234
	v_exp_f32_e32 v128, v128
	v_sub_f32_e32 v112, v48, v234
	v_exp_f32_e32 v112, v112
	v_sub_f32_e32 v129, v65, v234
	v_exp_f32_e32 v129, v129
	v_sub_f32_e32 v113, v49, v234
	v_exp_f32_e32 v113, v113
	v_sub_f32_e32 v130, v66, v234
	v_exp_f32_e32 v130, v130
	v_sub_f32_e32 v114, v50, v234
	v_exp_f32_e32 v114, v114
	v_sub_f32_e32 v131, v67, v234
	v_exp_f32_e32 v131, v131
	v_sub_f32_e32 v115, v51, v234
	v_exp_f32_e32 v115, v115
	v_sub_f32_e32 v132, v68, v234
	v_exp_f32_e32 v132, v132
	v_sub_f32_e32 v116, v52, v234
	v_exp_f32_e32 v116, v116
	v_sub_f32_e32 v133, v69, v234
	v_exp_f32_e32 v133, v133
	v_sub_f32_e32 v117, v53, v234
	v_exp_f32_e32 v117, v117
	v_sub_f32_e32 v134, v70, v234
	v_exp_f32_e32 v134, v134
	v_sub_f32_e32 v118, v54, v234
	v_exp_f32_e32 v118, v118
	v_sub_f32_e32 v135, v71, v234
	v_exp_f32_e32 v135, v135
	v_sub_f32_e32 v119, v55, v234
	v_exp_f32_e32 v119, v119
	v_sub_f32_e32 v136, v72, v234
	v_exp_f32_e32 v136, v136
	v_sub_f32_e32 v120, v56, v234
	v_exp_f32_e32 v120, v120
	v_sub_f32_e32 v137, v73, v234
	v_exp_f32_e32 v137, v137
	v_sub_f32_e32 v121, v57, v234
	v_exp_f32_e32 v121, v121
	v_sub_f32_e32 v138, v74, v234
	v_exp_f32_e32 v138, v138
	v_sub_f32_e32 v122, v58, v234
	v_exp_f32_e32 v122, v122
	v_sub_f32_e32 v139, v75, v234
	v_exp_f32_e32 v139, v139
	v_sub_f32_e32 v123, v59, v234
	v_exp_f32_e32 v123, v123
	v_sub_f32_e32 v140, v76, v234
	v_exp_f32_e32 v140, v140
	v_sub_f32_e32 v124, v60, v234
	v_exp_f32_e32 v124, v124
	v_sub_f32_e32 v141, v77, v234
	v_exp_f32_e32 v141, v141
	v_sub_f32_e32 v125, v61, v234
	v_exp_f32_e32 v125, v125
	v_sub_f32_e32 v142, v78, v234
	v_exp_f32_e32 v142, v142
	v_sub_f32_e32 v126, v62, v234
	v_exp_f32_e32 v126, v126
	v_sub_f32_e32 v143, v79, v234
	v_exp_f32_e32 v143, v143
	v_sub_f32_e32 v127, v63, v234
	v_exp_f32_e32 v127, v127
	v_pk_mul_f32 v[16:17], v[16:17], v[6:7] op_sel_hi:[1,0]
	v_pk_mul_f32 v[18:19], v[18:19], v[6:7] op_sel_hi:[1,0]
	v_pk_mul_f32 v[20:21], v[20:21], v[6:7] op_sel_hi:[1,0]
	v_pk_mul_f32 v[22:23], v[22:23], v[6:7] op_sel_hi:[1,0]
	v_pk_mul_f32 v[24:25], v[24:25], v[6:7] op_sel_hi:[1,0]
	v_pk_mul_f32 v[26:27], v[26:27], v[6:7] op_sel_hi:[1,0]
	v_pk_mul_f32 v[28:29], v[28:29], v[6:7] op_sel_hi:[1,0]
	v_pk_mul_f32 v[30:31], v[30:31], v[6:7] op_sel_hi:[1,0]
	v_pk_mul_f32 v[32:33], v[32:33], v[6:7] op_sel_hi:[1,0]
	v_pk_mul_f32 v[34:35], v[34:35], v[6:7] op_sel_hi:[1,0]
	v_pk_mul_f32 v[36:37], v[36:37], v[6:7] op_sel_hi:[1,0]
	v_pk_mul_f32 v[38:39], v[38:39], v[6:7] op_sel_hi:[1,0]
	v_pk_mul_f32 v[40:41], v[40:41], v[6:7] op_sel_hi:[1,0]
	v_pk_mul_f32 v[42:43], v[42:43], v[6:7] op_sel_hi:[1,0]
	v_pk_mul_f32 v[44:45], v[44:45], v[6:7] op_sel_hi:[1,0]
	v_pk_mul_f32 v[46:47], v[46:47], v[6:7] op_sel_hi:[1,0]
	s_branch .Lm01_pv

; #define LAS __attribute__((address_space(3)))
; template <int MODE  > ...
;     ...
;         if (has_next) {
;             LAS bf16_t* kb = (LAS bf16_t*)(lds + A_KBUF) + (cur ^ 1) * 64 * KPITCH;
;             *(LAS u32x4*)(kb + skey * KPITCH + schunk * 8) = kreg;
;             if (NEEDV) { LAS bf16_t* vb = (LAS bf16_t*)(lds + A_VBUF) + (cur ^ 1) * 64 * VPITCH;
;                 *(LAS u32x4*)(vb + skey * VPITCH + schunk * 8) = vreg; }
;         }
;         __syncthreads();
;         if (!has_next) break;
;         j = jn; cur ^= 1;
.Lm01_w1:
	ds_write_b128 v214, v[160:163]
	ds_write_b128 v215, v[164:167] offset:18432
.Lm0_bot1:
	s_waitcnt lgkmcnt(0)
	s_barrier
	s_cmp_eq_u32 s20, 0
	s_cbranch_scc1 .Lm0_exit
	s_mov_b32 s90, s89
	s_mov_b32 s89, s91
	s_mov_b32 s20, s21
	s_branch .LBB0_146

; #define LAS __attribute__((address_space(3)))
; template <int MODE  > ...
;     ...
;         const bool has_next = rem != 0ull; int jn = 0;
;         if (has_next) { jn = 63 - __builtin_clzll(rem); rem &= ~(1ull << jn);
;             kreg = *(const u32x4*)(Kg + (size_t)(64 * jn + skey) * 128 + schunk * 8);
;             if (NEEDV) vreg = *(const u32x4*)(Vg + (size_t)(64 * jn + skey) * 128 + schunk * 8); }
;         const bool selbit = (MODE == 1) ? (((selmask >> j) & 1ull) != 0ull) : true;
;         bool active = true;
;         if (MODE == 1) active = __builtin_amdgcn_ballot_w64(selbit) != 0ull;
;         if (active) {
;             const LAS bf16_t* kb = (const LAS bf16_t*)(lds + A_KBUF) + cur * 64 * KPITCH;
;             constexpr int STEP = CMPM ? 16 : 1;
;             const int Bint = CMPM ? (1024 * j + 31 - t + 64 * h) : (64 * j - t + 4 * h);
;             const float sl = slope2 * (float)STEP;
;             const float mref = st.m; const bool fresh = !(mref > -1e28f);
;             const float mest = fresh ? 0.f : mref;
;             const float basef = selbit ? (slope2 * (float)Bint - mest) : -1e30f;
;             int ptype;
;             if (MODE == 1) ptype = (j == cblk) ? 1 : 0;
;             else if (MODE == 2) ptype = (j == cblk) ? 1 : ((j == cblk - 8) ? 2 : 0);
;             else ptype = (64 * j + 63 <= 4 * cblk - 2) ? 0 : 1;
;             f32x16 s0, s1;
;             { const float sl2 = sl + sl, sl3 = sl2 + sl;
; #pragma unroll
;               for (int g8 = 0; g8 < 4; ++g8) {
;                   const float b0 = __builtin_fmaf(sl, (float)(8 * g8), basef), b1 = __builtin_fmaf(sl, (float)(8 * g8 + 32), basef);
;                   s0[4 * g8] = b0; s0[4 * g8 + 1] = b0 + sl; s0[4 * g8 + 2] = b0 + sl2; s0[4 * g8 + 3] = b0 + sl3;
;                   s1[4 * g8] = b1; s1[4 * g8 + 1] = b1 + sl; s1[4 * g8 + 2] = b1 + sl2; s1[4 * g8 + 3] = b1 + sl3;
;               } }
;             if (ptype == 1) {
;                 const float thr = 0.5f * slope2 - mest;
; #pragma unroll
;                 for (int i = 0; i < 16; ++i) { s0[i] = (s0[i] < thr) ? s0[i] : -1e30f; s1[i] = (s1[i] < thr) ? s1[i] : -1e30f; }
.LBB0_248:
	s_mov_b32 s21, 0
	s_cmp_eq_u64 s[18:19], 0
	s_cbranch_scc1 .Lm10_noload
	s_flbit_i32_b64 s4, s[18:19]
	s_xor_b32 s4, s4, 63
	s_lshl_b64 vcc, 1, s4
	s_andn2_b64 s[18:19], s[18:19], vcc
	s_mov_b32 s21, 1
	v_lshl_add_u32 v2, s4, 6, v164
	v_ashrrev_i32_e32 v3, 31, v2
	v_lshlrev_b64 v[2:3], 8, v[2:3]
	v_lshl_add_u64 v[4:5], v[160:161], 0, v[2:3]
	v_lshl_add_u64 v[2:3], v[142:143], 0, v[2:3]
	global_load_dwordx4 v[130:133], v[4:5], off
	global_load_dwordx4 v[134:137], v[2:3], off
.Lm10_noload:
.Lm1_body0:
	v_lshrrev_b64 v[2:3], s68, v[140:141]
	v_and_b32_e32 v1, 1, v2
	v_cmp_eq_u32_e64 s[16:17], 1, v1
	v_cmp_ne_u32_e32 vcc, 0, v1
	s_cbranch_vccz .Lm1_stage0
	ds_read_b128 v[66:69], v191
	ds_read_b128 v[70:73], v191 offset:4608
	ds_read_b128 v[74:77], v191 offset:32
	ds_read_b128 v[78:81], v191 offset:4640
	ds_read_b128 v[82:85], v191 offset:64
	ds_read_b128 v[86:89], v191 offset:4672
	ds_read_b128 v[90:93], v191 offset:96
	ds_read_b128 v[94:97], v191 offset:4704
	v_lshl_add_u32 v1, s68, 6, v190
	v_cvt_f32_i32_e32 v2, v1
	v_cmp_nlt_f32_e64 s[14:15], s71, v194
	s_cmp_lg_u32 s68, s83
	s_nop 0
	v_cndmask_b32_e64 v1, v194, 0, s[14:15]
	v_fma_f32 v2, v186, v2, -v1
	v_cndmask_b32_e64 v14, v241, v2, s[16:17]
	v_fma_f32 v50, 0, v186, v14
	v_fmamk_f32 v54, v186, 0x41000000, v14
	v_fmamk_f32 v58, v186, 0x41800000, v14
	v_fmamk_f32 v62, v186, 0x41c00000, v14
	v_fmamk_f32 v2, v186, 0x42000000, v14
	v_fmamk_f32 v6, v186, 0x42200000, v14
	v_fmamk_f32 v10, v186, 0x42400000, v14
	v_fmac_f32_e32 v14, 0x42600000, v186
	v_add_f32_e32 v51, v186, v50
	v_add_f32_e32 v52, v187, v50
	v_add_f32_e32 v53, v163, v50
	v_add_f32_e32 v55, v186, v54
	v_add_f32_e32 v56, v187, v54
	v_add_f32_e32 v57, v163, v54
	v_add_f32_e32 v59, v186, v58
	v_add_f32_e32 v60, v187, v58
	v_add_f32_e32 v61, v163, v58
	v_add_f32_e32 v63, v186, v62
	v_add_f32_e32 v64, v187, v62
	v_add_f32_e32 v65, v163, v62
	v_add_f32_e32 v3, v186, v2
	v_add_f32_e32 v4, v187, v2
	v_add_f32_e32 v5, v163, v2
	v_add_f32_e32 v7, v186, v6
	v_add_f32_e32 v8, v187, v6
	v_add_f32_e32 v9, v163, v6
	v_add_f32_e32 v11, v186, v10
	v_add_f32_e32 v12, v187, v10
	v_add_f32_e32 v13, v163, v10
	v_add_f32_e32 v15, v186, v14
	v_add_f32_e32 v16, v187, v14
	v_add_f32_e32 v17, v163, v14
	s_cbranch_scc1 .Lm10_qk
	v_sub_f32_e32 v254, v189, v1
	v_cmp_lt_f32_e32 vcc, v50, v254
	s_nop 1
	v_cndmask_b32_e32 v50, v241, v50, vcc
	v_cmp_lt_f32_e32 vcc, v51, v254
	s_nop 1
	v_cndmask_b32_e32 v51, v241, v51, vcc
	v_cmp_lt_f32_e32 vcc, v52, v254
	s_nop 1
	v_cndmask_b32_e32 v52, v241, v52, vcc
	v_cmp_lt_f32_e32 vcc, v53, v254
	s_nop 1
	v_cndmask_b32_e32 v53, v241, v53, vcc
	v_cmp_lt_f32_e32 vcc, v54, v254
	s_nop 1
	v_cndmask_b32_e32 v54, v241, v54, vcc
	v_cmp_lt_f32_e32 vcc, v55, v254
	s_nop 1
	v_cndmask_b32_e32 v55, v241, v55, vcc
	v_cmp_lt_f32_e32 vcc, v56, v254
	s_nop 1
	v_cndmask_b32_e32 v56, v241, v56, vcc
	v_cmp_lt_f32_e32 vcc, v57, v254
	s_nop 1
	v_cndmask_b32_e32 v57, v241, v57, vcc
	v_cmp_lt_f32_e32 vcc, v58, v254
	s_nop 1
	v_cndmask_b32_e32 v58, v241, v58, vcc
	v_cmp_lt_f32_e32 vcc, v59, v254
	s_nop 1
	v_cndmask_b32_e32 v59, v241, v59, vcc
	v_cmp_lt_f32_e32 vcc, v60, v254
	s_nop 1
	v_cndmask_b32_e32 v60, v241, v60, vcc
	v_cmp_lt_f32_e32 vcc, v61, v254
	s_nop 1
	v_cndmask_b32_e32 v61, v241, v61, vcc
	v_cmp_lt_f32_e32 vcc, v62, v254
	s_nop 1
	v_cndmask_b32_e32 v62, v241, v62, vcc
	v_cmp_lt_f32_e32 vcc, v63, v254
	s_nop 1
	v_cndmask_b32_e32 v63, v241, v63, vcc
	v_cmp_lt_f32_e32 vcc, v64, v254
	s_nop 1
	v_cndmask_b32_e32 v64, v241, v64, vcc
	v_cmp_lt_f32_e32 vcc, v65, v254
	s_nop 1
	v_cndmask_b32_e32 v65, v241, v65, vcc
	v_cmp_lt_f32_e32 vcc, v2, v254
	s_nop 1
	v_cndmask_b32_e32 v2, v241, v2, vcc
	v_cmp_lt_f32_e32 vcc, v3, v254
	s_nop 1
	v_cndmask_b32_e32 v3, v241, v3, vcc
	v_cmp_lt_f32_e32 vcc, v4, v254
	s_nop 1
	v_cndmask_b32_e32 v4, v241, v4, vcc
	v_cmp_lt_f32_e32 vcc, v5, v254
	s_nop 1
	v_cndmask_b32_e32 v5, v241, v5, vcc
	v_cmp_lt_f32_e32 vcc, v6, v254
	s_nop 1
	v_cndmask_b32_e32 v6, v241, v6, vcc
	v_cmp_lt_f32_e32 vcc, v7, v254
	s_nop 1
	v_cndmask_b32_e32 v7, v241, v7, vcc
	v_cmp_lt_f32_e32 vcc, v8, v254
	s_nop 1
	v_cndmask_b32_e32 v8, v241, v8, vcc
	v_cmp_lt_f32_e32 vcc, v9, v254
	s_nop 1
	v_cndmask_b32_e32 v9, v241, v9, vcc
	v_cmp_lt_f32_e32 vcc, v10, v254
	s_nop 1
	v_cndmask_b32_e32 v10, v241, v10, vcc
	v_cmp_lt_f32_e32 vcc, v11, v254
	s_nop 1
	v_cndmask_b32_e32 v11, v241, v11, vcc
	v_cmp_lt_f32_e32 vcc, v12, v254
	s_nop 1
	v_cndmask_b32_e32 v12, v241, v12, vcc
	v_cmp_lt_f32_e32 vcc, v13, v254
	s_nop 1
	v_cndmask_b32_e32 v13, v241, v13, vcc
	v_cmp_lt_f32_e32 vcc, v14, v254
	s_nop 1
	v_cndmask_b32_e32 v14, v241, v14, vcc
	v_cmp_lt_f32_e32 vcc, v15, v254
	s_nop 1
	v_cndmask_b32_e32 v15, v241, v15, vcc
	v_cmp_lt_f32_e32 vcc, v16, v254
	s_nop 1
	v_cndmask_b32_e32 v16, v241, v16, vcc
	v_cmp_lt_f32_e32 vcc, v17, v254
	s_nop 1
	v_cndmask_b32_e32 v17, v241, v17, vcc
; #define LAS __attribute__((address_space(3)))
; __device__ __forceinline__ float shflx(float v, int mask, int lane) { return __builtin_bit_cast(float, __builtin_amdgcn_ds_bpermute(((lane ^ mask) & 63) << 2, __builtin_bit_cast(int, v))); }
; template <int MODE  > ...
;     ...
;             for (int kk = 0; kk < 4; ++kk) {
;                 const bf16x8 k0 = *(const LAS bf16x8*)(kb + col * KPITCH + kk * 16 + h * 8);
;                 const bf16x8 k1 = *(const LAS bf16x8*)(kb + (32 + col) * KPITCH + kk * 16 + h * 8);
;                 s0 = __builtin_amdgcn_mfma_f32_32x32x16_bf16(k0, qf[kk], s0, 0, 0, 0);
;                 s1 = __builtin_amdgcn_mfma_f32_32x32x16_bf16(k1, qf[kk], s1, 0, 0, 0);
;             }
;             if (MODE != 3) {
;                 float mx = fmaxf(s0[0], s1[0]);
; #pragma unroll
;                 for (int i = 1; i < 16; ++i) mx = fmaxf(mx, fmaxf(s0[i], s1[i]));
;                 mx = fmaxf(mx, shflx(mx, 32, lane));
;                 float alpha = 1.f;
;                 if (__builtin_amdgcn_ballot_w64(fresh || mx > 0.f) != 0ull) {
;                     const float moldr = fresh ? -1e29f : 0.f, mnewr = fmaxf(moldr, mx);
;                     alpha = __builtin_amdgcn_exp2f(moldr - mnewr);
;                     st.m = mest + mnewr;
; #pragma unroll
;                     for (int i = 0; i < 16; ++i) { s0[i] = __builtin_amdgcn_exp2f(s0[i] - mnewr); s1[i] = __builtin_amdgcn_exp2f(s1[i] - mnewr); }
;                     st.o0 *= alpha; st.o1 *= alpha;
.Lm10_qk:
	s_waitcnt lgkmcnt(6)
	v_mfma_f32_32x32x16_bf16 v[50:65], v[66:69], v[144:147], v[50:65]
	v_mfma_f32_32x32x16_bf16 v[2:17], v[70:73], v[144:147], v[2:17]
	s_waitcnt lgkmcnt(4)
	v_mfma_f32_32x32x16_bf16 v[50:65], v[74:77], v[148:151], v[50:65]
	v_mfma_f32_32x32x16_bf16 v[2:17], v[78:81], v[148:151], v[2:17]
	s_waitcnt lgkmcnt(2)
	v_mfma_f32_32x32x16_bf16 v[50:65], v[82:85], v[152:155], v[50:65]
	v_mfma_f32_32x32x16_bf16 v[2:17], v[86:89], v[152:155], v[2:17]
	s_waitcnt lgkmcnt(0)
	v_mfma_f32_32x32x16_bf16 v[50:65], v[90:93], v[156:159], v[50:65]
	v_mfma_f32_32x32x16_bf16 v[2:17], v[94:97], v[156:159], v[2:17]
	ds_read_b64_tr_b16 v[66:67], v192 offset:18432
	ds_read_b64_tr_b16 v[68:69], v192 offset:19968
	ds_read_b64_tr_b16 v[70:71], v192 offset:18496
	ds_read_b64_tr_b16 v[72:73], v192 offset:20032
	ds_read_b64_tr_b16 v[74:75], v192 offset:21504
	ds_read_b64_tr_b16 v[76:77], v192 offset:23040
	ds_read_b64_tr_b16 v[78:79], v192 offset:21568
	ds_read_b64_tr_b16 v[80:81], v192 offset:23104
	s_nop 3
	v_max3_f32 v234, v50, v51, v52
	v_max3_f32 v234, v234, v53, v54
	v_max3_f32 v234, v234, v55, v56
	v_max3_f32 v234, v234, v57, v58
	v_max3_f32 v234, v234, v59, v60
	v_max3_f32 v234, v234, v61, v62
	v_max3_f32 v234, v234, v63, v64
	v_max3_f32 v235, v2, v3, v4
	v_max3_f32 v235, v235, v5, v6
	v_max3_f32 v235, v235, v7, v8
	v_max3_f32 v235, v235, v9, v10
	v_max3_f32 v235, v235, v11, v12
	v_max3_f32 v235, v235, v13, v14
	v_max3_f32 v235, v235, v15, v16
	v_max3_f32 v234, v234, v65, v17
	v_max_f32_e32 v234, v234, v235
	v_mov_b32_e32 v235, v234
	s_waitcnt lgkmcnt(7)
	ds_read_b64_tr_b16 v[82:83], v192 offset:24576
	ds_read_b64_tr_b16 v[84:85], v192 offset:26112
	ds_read_b64_tr_b16 v[86:87], v192 offset:24640
	ds_read_b64_tr_b16 v[88:89], v192 offset:26176
	ds_read_b64_tr_b16 v[90:91], v192 offset:27648
	ds_read_b64_tr_b16 v[92:93], v192 offset:29184
	ds_read_b64_tr_b16 v[94:95], v192 offset:27712
	ds_read_b64_tr_b16 v[96:97], v192 offset:29248
	v_permlane32_swap_b32_e32 v235, v234
	v_max_f32_e32 v234, v234, v235
	v_cmp_lt_f32_e32 vcc, 0, v234
	s_or_b64 vcc, s[14:15], vcc
	s_cbranch_vccz .Lm10_norescale
	v_cndmask_b32_e64 v235, 0, v242, s[14:15]
	v_max_f32_e32 v234, v235, v234
	v_sub_f32_e32 v235, v235, v234
	v_exp_f32_e32 v162, v235
	v_add_f32_e32 v194, v1, v234
	v_sub_f32_e32 v114, v50, v234
	v_exp_f32_e32 v114, v114
	v_sub_f32_e32 v98, v2, v234
	v_exp_f32_e32 v98, v98
	v_sub_f32_e32 v115, v51, v234
	v_exp_f32_e32 v115, v115
	v_sub_f32_e32 v99, v3, v234
	v_exp_f32_e32 v99, v99
	v_sub_f32_e32 v116, v52, v234
	v_exp_f32_e32 v116, v116
	v_sub_f32_e32 v100, v4, v234
	v_exp_f32_e32 v100, v100
	v_sub_f32_e32 v117, v53, v234
	v_exp_f32_e32 v117, v117
	v_sub_f32_e32 v101, v5, v234
	v_exp_f32_e32 v101, v101
	v_sub_f32_e32 v118, v54, v234
	v_exp_f32_e32 v118, v118
	v_sub_f32_e32 v102, v6, v234
	v_exp_f32_e32 v102, v102
	v_sub_f32_e32 v119, v55, v234
	v_exp_f32_e32 v119, v119
	v_sub_f32_e32 v103, v7, v234
	v_exp_f32_e32 v103, v103
	v_sub_f32_e32 v120, v56, v234
	v_exp_f32_e32 v120, v120
	v_sub_f32_e32 v104, v8, v234
	v_exp_f32_e32 v104, v104
	v_sub_f32_e32 v121, v57, v234
	v_exp_f32_e32 v121, v121
	v_sub_f32_e32 v105, v9, v234
	v_exp_f32_e32 v105, v105
	v_sub_f32_e32 v122, v58, v234
	v_exp_f32_e32 v122, v122
	v_sub_f32_e32 v106, v10, v234
	v_exp_f32_e32 v106, v106
	v_sub_f32_e32 v123, v59, v234
	v_exp_f32_e32 v123, v123
	v_sub_f32_e32 v107, v11, v234
	v_exp_f32_e32 v107, v107
	v_sub_f32_e32 v124, v60, v234
	v_exp_f32_e32 v124, v124
	v_sub_f32_e32 v108, v12, v234
	v_exp_f32_e32 v108, v108
	v_sub_f32_e32 v125, v61, v234
	v_exp_f32_e32 v125, v125
	v_sub_f32_e32 v109, v13, v234
	v_exp_f32_e32 v109, v109
	v_sub_f32_e32 v126, v62, v234
	v_exp_f32_e32 v126, v126
	v_sub_f32_e32 v110, v14, v234
	v_exp_f32_e32 v110, v110
	v_sub_f32_e32 v127, v63, v234
	v_exp_f32_e32 v127, v127
	v_sub_f32_e32 v111, v15, v234
	v_exp_f32_e32 v111, v111
	v_sub_f32_e32 v128, v64, v234
	v_exp_f32_e32 v128, v128
	v_sub_f32_e32 v112, v16, v234
	v_exp_f32_e32 v112, v112
	v_sub_f32_e32 v129, v65, v234
	v_exp_f32_e32 v129, v129
	v_sub_f32_e32 v113, v17, v234
	v_exp_f32_e32 v113, v113
	v_pk_mul_f32 v[18:19], v[18:19], v[162:163] op_sel_hi:[1,0]
	v_pk_mul_f32 v[20:21], v[20:21], v[162:163] op_sel_hi:[1,0]
	v_pk_mul_f32 v[22:23], v[22:23], v[162:163] op_sel_hi:[1,0]
	v_pk_mul_f32 v[24:25], v[24:25], v[162:163] op_sel_hi:[1,0]
	v_pk_mul_f32 v[26:27], v[26:27], v[162:163] op_sel_hi:[1,0]
	v_pk_mul_f32 v[28:29], v[28:29], v[162:163] op_sel_hi:[1,0]
	v_pk_mul_f32 v[30:31], v[30:31], v[162:163] op_sel_hi:[1,0]
	v_pk_mul_f32 v[32:33], v[32:33], v[162:163] op_sel_hi:[1,0]
	v_pk_mul_f32 v[34:35], v[34:35], v[162:163] op_sel_hi:[1,0]
	v_pk_mul_f32 v[36:37], v[36:37], v[162:163] op_sel_hi:[1,0]
	v_pk_mul_f32 v[38:39], v[38:39], v[162:163] op_sel_hi:[1,0]
	v_pk_mul_f32 v[40:41], v[40:41], v[162:163] op_sel_hi:[1,0]
	v_pk_mul_f32 v[42:43], v[42:43], v[162:163] op_sel_hi:[1,0]
	v_pk_mul_f32 v[44:45], v[44:45], v[162:163] op_sel_hi:[1,0]
	v_pk_mul_f32 v[46:47], v[46:47], v[162:163] op_sel_hi:[1,0]
	v_pk_mul_f32 v[48:49], v[48:49], v[162:163] op_sel_hi:[1,0]
	s_branch .Lm10_pv

; #define LAS __attribute__((address_space(3)))
; template <int MODE  > ...
;     ...
;         const bool has_next = rem != 0ull; int jn = 0;
;         if (has_next) { jn = 63 - __builtin_clzll(rem); rem &= ~(1ull << jn);
;             kreg = *(const u32x4*)(Kg + (size_t)(64 * jn + skey) * 128 + schunk * 8);
;             if (NEEDV) vreg = *(const u32x4*)(Vg + (size_t)(64 * jn + skey) * 128 + schunk * 8); }
;         const bool selbit = (MODE == 1) ? (((selmask >> j) & 1ull) != 0ull) : true;
;         bool active = true;
;         if (MODE == 1) active = __builtin_amdgcn_ballot_w64(selbit) != 0ull;
;         if (active) {
;             const LAS bf16_t* kb = (const LAS bf16_t*)(lds + A_KBUF) + cur * 64 * KPITCH;
;             constexpr int STEP = CMPM ? 16 : 1;
;             const int Bint = CMPM ? (1024 * j + 31 - t + 64 * h) : (64 * j - t + 4 * h);
;             const float sl = slope2 * (float)STEP;
;             const float mref = st.m; const bool fresh = !(mref > -1e28f);
;             const float mest = fresh ? 0.f : mref;
;             const float basef = selbit ? (slope2 * (float)Bint - mest) : -1e30f;
;             int ptype;
;             if (MODE == 1) ptype = (j == cblk) ? 1 : 0;
;             else if (MODE == 2) ptype = (j == cblk) ? 1 : ((j == cblk - 8) ? 2 : 0);
;             else ptype = (64 * j + 63 <= 4 * cblk - 2) ? 0 : 1;
;             f32x16 s0, s1;
;             { const float sl2 = sl + sl, sl3 = sl2 + sl;
; #pragma unroll
;               for (int g8 = 0; g8 < 4; ++g8) {
;                   const float b0 = __builtin_fmaf(sl, (float)(8 * g8), basef), b1 = __builtin_fmaf(sl, (float)(8 * g8 + 32), basef);
;                   s0[4 * g8] = b0; s0[4 * g8 + 1] = b0 + sl; s0[4 * g8 + 2] = b0 + sl2; s0[4 * g8 + 3] = b0 + sl3;
;                   s1[4 * g8] = b1; s1[4 * g8 + 1] = b1 + sl; s1[4 * g8 + 2] = b1 + sl2; s1[4 * g8 + 3] = b1 + sl3;
;               } }
;             if (ptype == 1) {
;     ...
;         if (has_next) {
;             LAS bf16_t* kb = (LAS bf16_t*)(lds + A_KBUF) + (cur ^ 1) * 64 * KPITCH;
;             *(LAS u32x4*)(kb + skey * KPITCH + schunk * 8) = kreg;
;             if (NEEDV) { LAS bf16_t* vb = (LAS bf16_t*)(lds + A_VBUF) + (cur ^ 1) * 64 * VPITCH;
;                 *(LAS u32x4*)(vb + skey * VPITCH + schunk * 8) = vreg; }
;         }
;         __syncthreads();
;         if (!has_next) break;
;         j = jn; cur ^= 1;
;     }
.Lm10_w1:
	ds_write_b128 v166, v[226:229] offset:9216
	ds_write_b128 v167, v[230:233] offset:30720
.Lm1_bot0:
	s_waitcnt lgkmcnt(0)
	s_barrier
	s_cmp_eq_u32 s20, 0
	s_cbranch_scc1 .Lm1_exit
	s_mov_b32 s68, s62
	s_mov_b32 s62, s4
	s_mov_b32 s20, s21
.Lm1_loop1:
	s_mov_b32 s21, 0
	s_cmp_eq_u64 s[18:19], 0
	s_cbranch_scc1 .Lm11_noload
	s_flbit_i32_b64 s4, s[18:19]
	s_xor_b32 s4, s4, 63
	s_lshl_b64 vcc, 1, s4
	s_andn2_b64 s[18:19], s[18:19], vcc
	s_mov_b32 s21, 1
	v_lshl_add_u32 v2, s4, 6, v164
	v_ashrrev_i32_e32 v3, 31, v2
	v_lshlrev_b64 v[2:3], 8, v[2:3]
	v_lshl_add_u64 v[4:5], v[160:161], 0, v[2:3]
	v_lshl_add_u64 v[2:3], v[142:143], 0, v[2:3]
	global_load_dwordx4 v[226:229], v[4:5], off
	global_load_dwordx4 v[230:233], v[2:3], off
.Lm11_noload:
.Lm1_body1:
	v_lshrrev_b64 v[2:3], s68, v[140:141]
	v_and_b32_e32 v1, 1, v2
	v_cmp_eq_u32_e64 s[16:17], 1, v1
	v_cmp_ne_u32_e32 vcc, 0, v1
	s_cbranch_vccz .Lm1_stage1
	ds_read_b128 v[66:69], v191 offset:9216
	ds_read_b128 v[70:73], v191 offset:13824
	ds_read_b128 v[74:77], v191 offset:9248
	ds_read_b128 v[78:81], v191 offset:13856
	ds_read_b128 v[82:85], v191 offset:9280
	ds_read_b128 v[86:89], v191 offset:13888
	ds_read_b128 v[90:93], v191 offset:9312
	ds_read_b128 v[94:97], v191 offset:13920
	v_lshl_add_u32 v1, s68, 6, v190
	v_cvt_f32_i32_e32 v2, v1
	v_cmp_nlt_f32_e64 s[14:15], s71, v194
	s_cmp_lg_u32 s68, s83
	s_nop 0
	v_cndmask_b32_e64 v1, v194, 0, s[14:15]
	v_fma_f32 v2, v186, v2, -v1
	v_cndmask_b32_e64 v14, v241, v2, s[16:17]
	v_fma_f32 v50, 0, v186, v14
	v_fmamk_f32 v54, v186, 0x41000000, v14
	v_fmamk_f32 v58, v186, 0x41800000, v14
	v_fmamk_f32 v62, v186, 0x41c00000, v14
	v_fmamk_f32 v2, v186, 0x42000000, v14
	v_fmamk_f32 v6, v186, 0x42200000, v14
	v_fmamk_f32 v10, v186, 0x42400000, v14
	v_fmac_f32_e32 v14, 0x42600000, v186
	v_add_f32_e32 v51, v186, v50
	v_add_f32_e32 v52, v187, v50
	v_add_f32_e32 v53, v163, v50
	v_add_f32_e32 v55, v186, v54
	v_add_f32_e32 v56, v187, v54
	v_add_f32_e32 v57, v163, v54
	v_add_f32_e32 v59, v186, v58
	v_add_f32_e32 v60, v187, v58
	v_add_f32_e32 v61, v163, v58
	v_add_f32_e32 v63, v186, v62
	v_add_f32_e32 v64, v187, v62
	v_add_f32_e32 v65, v163, v62
	v_add_f32_e32 v3, v186, v2
	v_add_f32_e32 v4, v187, v2
	v_add_f32_e32 v5, v163, v2
	v_add_f32_e32 v7, v186, v6
	v_add_f32_e32 v8, v187, v6
	v_add_f32_e32 v9, v163, v6
	v_add_f32_e32 v11, v186, v10
	v_add_f32_e32 v12, v187, v10
	v_add_f32_e32 v13, v163, v10
	v_add_f32_e32 v15, v186, v14
	v_add_f32_e32 v16, v187, v14
	v_add_f32_e32 v17, v163, v14
	s_cbranch_scc1 .Lm11_qk
	v_sub_f32_e32 v254, v189, v1
	v_cmp_lt_f32_e32 vcc, v50, v254
	s_nop 1
	v_cndmask_b32_e32 v50, v241, v50, vcc
	v_cmp_lt_f32_e32 vcc, v51, v254
	s_nop 1
	v_cndmask_b32_e32 v51, v241, v51, vcc
	v_cmp_lt_f32_e32 vcc, v52, v254
	s_nop 1
	v_cndmask_b32_e32 v52, v241, v52, vcc
	v_cmp_lt_f32_e32 vcc, v53, v254
	s_nop 1
	v_cndmask_b32_e32 v53, v241, v53, vcc
	v_cmp_lt_f32_e32 vcc, v54, v254
	s_nop 1
	v_cndmask_b32_e32 v54, v241, v54, vcc
	v_cmp_lt_f32_e32 vcc, v55, v254
	s_nop 1
	v_cndmask_b32_e32 v55, v241, v55, vcc
	v_cmp_lt_f32_e32 vcc, v56, v254
	s_nop 1
	v_cndmask_b32_e32 v56, v241, v56, vcc
	v_cmp_lt_f32_e32 vcc, v57, v254
	s_nop 1
	v_cndmask_b32_e32 v57, v241, v57, vcc
	v_cmp_lt_f32_e32 vcc, v58, v254
	s_nop 1
	v_cndmask_b32_e32 v58, v241, v58, vcc
	v_cmp_lt_f32_e32 vcc, v59, v254
	s_nop 1
	v_cndmask_b32_e32 v59, v241, v59, vcc
	v_cmp_lt_f32_e32 vcc, v60, v254
	s_nop 1
	v_cndmask_b32_e32 v60, v241, v60, vcc
	v_cmp_lt_f32_e32 vcc, v61, v254
	s_nop 1
	v_cndmask_b32_e32 v61, v241, v61, vcc
	v_cmp_lt_f32_e32 vcc, v62, v254
	s_nop 1
	v_cndmask_b32_e32 v62, v241, v62, vcc
	v_cmp_lt_f32_e32 vcc, v63, v254
	s_nop 1
	v_cndmask_b32_e32 v63, v241, v63, vcc
	v_cmp_lt_f32_e32 vcc, v64, v254
	s_nop 1
	v_cndmask_b32_e32 v64, v241, v64, vcc
	v_cmp_lt_f32_e32 vcc, v65, v254
	s_nop 1
	v_cndmask_b32_e32 v65, v241, v65, vcc
	v_cmp_lt_f32_e32 vcc, v2, v254
	s_nop 1
	v_cndmask_b32_e32 v2, v241, v2, vcc
	v_cmp_lt_f32_e32 vcc, v3, v254
	s_nop 1
	v_cndmask_b32_e32 v3, v241, v3, vcc
	v_cmp_lt_f32_e32 vcc, v4, v254
	s_nop 1
	v_cndmask_b32_e32 v4, v241, v4, vcc
	v_cmp_lt_f32_e32 vcc, v5, v254
	s_nop 1
	v_cndmask_b32_e32 v5, v241, v5, vcc
	v_cmp_lt_f32_e32 vcc, v6, v254
	s_nop 1
	v_cndmask_b32_e32 v6, v241, v6, vcc
	v_cmp_lt_f32_e32 vcc, v7, v254
	s_nop 1
	v_cndmask_b32_e32 v7, v241, v7, vcc
	v_cmp_lt_f32_e32 vcc, v8, v254
	s_nop 1
	v_cndmask_b32_e32 v8, v241, v8, vcc
	v_cmp_lt_f32_e32 vcc, v9, v254
	s_nop 1
	v_cndmask_b32_e32 v9, v241, v9, vcc
	v_cmp_lt_f32_e32 vcc, v10, v254
	s_nop 1
	v_cndmask_b32_e32 v10, v241, v10, vcc
	v_cmp_lt_f32_e32 vcc, v11, v254
	s_nop 1
	v_cndmask_b32_e32 v11, v241, v11, vcc
	v_cmp_lt_f32_e32 vcc, v12, v254
	s_nop 1
	v_cndmask_b32_e32 v12, v241, v12, vcc
	v_cmp_lt_f32_e32 vcc, v13, v254
	s_nop 1
	v_cndmask_b32_e32 v13, v241, v13, vcc
	v_cmp_lt_f32_e32 vcc, v14, v254
	s_nop 1
	v_cndmask_b32_e32 v14, v241, v14, vcc
	v_cmp_lt_f32_e32 vcc, v15, v254
	s_nop 1
	v_cndmask_b32_e32 v15, v241, v15, vcc
	v_cmp_lt_f32_e32 vcc, v16, v254
	s_nop 1
	v_cndmask_b32_e32 v16, v241, v16, vcc
	v_cmp_lt_f32_e32 vcc, v17, v254
	s_nop 1
	v_cndmask_b32_e32 v17, v241, v17, vcc
; #define LAS __attribute__((address_space(3)))
; __device__ __forceinline__ float shflx(float v, int mask, int lane) { return __builtin_bit_cast(float, __builtin_amdgcn_ds_bpermute(((lane ^ mask) & 63) << 2, __builtin_bit_cast(int, v))); }
; template <int MODE  > ...
;     ...
;             for (int kk = 0; kk < 4; ++kk) {
;                 const bf16x8 k0 = *(const LAS bf16x8*)(kb + col * KPITCH + kk * 16 + h * 8);
;                 const bf16x8 k1 = *(const LAS bf16x8*)(kb + (32 + col) * KPITCH + kk * 16 + h * 8);
;                 s0 = __builtin_amdgcn_mfma_f32_32x32x16_bf16(k0, qf[kk], s0, 0, 0, 0);
;                 s1 = __builtin_amdgcn_mfma_f32_32x32x16_bf16(k1, qf[kk], s1, 0, 0, 0);
;             }
;             if (MODE != 3) {
;                 float mx = fmaxf(s0[0], s1[0]);
; #pragma unroll
;                 for (int i = 1; i < 16; ++i) mx = fmaxf(mx, fmaxf(s0[i], s1[i]));
;                 mx = fmaxf(mx, shflx(mx, 32, lane));
;                 float alpha = 1.f;
;                 if (__builtin_amdgcn_ballot_w64(fresh || mx > 0.f) != 0ull) {
;                     const float moldr = fresh ? -1e29f : 0.f, mnewr = fmaxf(moldr, mx);
;                     alpha = __builtin_amdgcn_exp2f(moldr - mnewr);
;                     st.m = mest + mnewr;
; #pragma unroll
;                     for (int i = 0; i < 16; ++i) { s0[i] = __builtin_amdgcn_exp2f(s0[i] - mnewr); s1[i] = __builtin_amdgcn_exp2f(s1[i] - mnewr); }
;                     st.o0 *= alpha; st.o1 *= alpha;
.Lm11_qk:
	s_waitcnt lgkmcnt(6)
	v_mfma_f32_32x32x16_bf16 v[50:65], v[66:69], v[144:147], v[50:65]
	v_mfma_f32_32x32x16_bf16 v[2:17], v[70:73], v[144:147], v[2:17]
	s_waitcnt lgkmcnt(4)
	v_mfma_f32_32x32x16_bf16 v[50:65], v[74:77], v[148:151], v[50:65]
	v_mfma_f32_32x32x16_bf16 v[2:17], v[78:81], v[148:151], v[2:17]
	s_waitcnt lgkmcnt(2)
	v_mfma_f32_32x32x16_bf16 v[50:65], v[82:85], v[152:155], v[50:65]
	v_mfma_f32_32x32x16_bf16 v[2:17], v[86:89], v[152:155], v[2:17]
	s_waitcnt lgkmcnt(0)
	v_mfma_f32_32x32x16_bf16 v[50:65], v[90:93], v[156:159], v[50:65]
	v_mfma_f32_32x32x16_bf16 v[2:17], v[94:97], v[156:159], v[2:17]
	ds_read_b64_tr_b16 v[66:67], v192 offset:30720
	ds_read_b64_tr_b16 v[68:69], v192 offset:32256
	ds_read_b64_tr_b16 v[70:71], v192 offset:30784
	ds_read_b64_tr_b16 v[72:73], v192 offset:32320
	ds_read_b64_tr_b16 v[74:75], v192 offset:33792
	ds_read_b64_tr_b16 v[76:77], v192 offset:35328
	ds_read_b64_tr_b16 v[78:79], v192 offset:33856
	ds_read_b64_tr_b16 v[80:81], v192 offset:35392
	s_nop 3
	v_max3_f32 v234, v50, v51, v52
	v_max3_f32 v234, v234, v53, v54
	v_max3_f32 v234, v234, v55, v56
	v_max3_f32 v234, v234, v57, v58
	v_max3_f32 v234, v234, v59, v60
	v_max3_f32 v234, v234, v61, v62
	v_max3_f32 v234, v234, v63, v64
	v_max3_f32 v235, v2, v3, v4
	v_max3_f32 v235, v235, v5, v6
	v_max3_f32 v235, v235, v7, v8
	v_max3_f32 v235, v235, v9, v10
	v_max3_f32 v235, v235, v11, v12
	v_max3_f32 v235, v235, v13, v14
	v_max3_f32 v235, v235, v15, v16
	v_max3_f32 v234, v234, v65, v17
	v_max_f32_e32 v234, v234, v235
	v_mov_b32_e32 v235, v234
	s_waitcnt lgkmcnt(7)
	ds_read_b64_tr_b16 v[82:83], v192 offset:36864
	ds_read_b64_tr_b16 v[84:85], v192 offset:38400
	ds_read_b64_tr_b16 v[86:87], v192 offset:36928
	ds_read_b64_tr_b16 v[88:89], v192 offset:38464
	ds_read_b64_tr_b16 v[90:91], v192 offset:39936
	ds_read_b64_tr_b16 v[92:93], v192 offset:41472
	ds_read_b64_tr_b16 v[94:95], v192 offset:40000
	ds_read_b64_tr_b16 v[96:97], v192 offset:41536
	v_permlane32_swap_b32_e32 v235, v234
	v_max_f32_e32 v234, v234, v235
	v_cmp_lt_f32_e32 vcc, 0, v234
	s_or_b64 vcc, s[14:15], vcc
	s_cbranch_vccz .Lm11_norescale
	v_cndmask_b32_e64 v235, 0, v242, s[14:15]
	v_max_f32_e32 v234, v235, v234
	v_sub_f32_e32 v235, v235, v234
	v_exp_f32_e32 v162, v235
	v_add_f32_e32 v194, v1, v234
	v_sub_f32_e32 v114, v50, v234
	v_exp_f32_e32 v114, v114
	v_sub_f32_e32 v98, v2, v234
	v_exp_f32_e32 v98, v98
	v_sub_f32_e32 v115, v51, v234
	v_exp_f32_e32 v115, v115
	v_sub_f32_e32 v99, v3, v234
	v_exp_f32_e32 v99, v99
	v_sub_f32_e32 v116, v52, v234
	v_exp_f32_e32 v116, v116
	v_sub_f32_e32 v100, v4, v234
	v_exp_f32_e32 v100, v100
	v_sub_f32_e32 v117, v53, v234
	v_exp_f32_e32 v117, v117
	v_sub_f32_e32 v101, v5, v234
	v_exp_f32_e32 v101, v101
	v_sub_f32_e32 v118, v54, v234
	v_exp_f32_e32 v118, v118
	v_sub_f32_e32 v102, v6, v234
	v_exp_f32_e32 v102, v102
	v_sub_f32_e32 v119, v55, v234
	v_exp_f32_e32 v119, v119
	v_sub_f32_e32 v103, v7, v234
	v_exp_f32_e32 v103, v103
	v_sub_f32_e32 v120, v56, v234
	v_exp_f32_e32 v120, v120
	v_sub_f32_e32 v104, v8, v234
	v_exp_f32_e32 v104, v104
	v_sub_f32_e32 v121, v57, v234
	v_exp_f32_e32 v121, v121
	v_sub_f32_e32 v105, v9, v234
	v_exp_f32_e32 v105, v105
	v_sub_f32_e32 v122, v58, v234
	v_exp_f32_e32 v122, v122
	v_sub_f32_e32 v106, v10, v234
	v_exp_f32_e32 v106, v106
	v_sub_f32_e32 v123, v59, v234
	v_exp_f32_e32 v123, v123
	v_sub_f32_e32 v107, v11, v234
	v_exp_f32_e32 v107, v107
	v_sub_f32_e32 v124, v60, v234
	v_exp_f32_e32 v124, v124
	v_sub_f32_e32 v108, v12, v234
	v_exp_f32_e32 v108, v108
	v_sub_f32_e32 v125, v61, v234
	v_exp_f32_e32 v125, v125
	v_sub_f32_e32 v109, v13, v234
	v_exp_f32_e32 v109, v109
	v_sub_f32_e32 v126, v62, v234
	v_exp_f32_e32 v126, v126
	v_sub_f32_e32 v110, v14, v234
	v_exp_f32_e32 v110, v110
	v_sub_f32_e32 v127, v63, v234
	v_exp_f32_e32 v127, v127
	v_sub_f32_e32 v111, v15, v234
	v_exp_f32_e32 v111, v111
	v_sub_f32_e32 v128, v64, v234
	v_exp_f32_e32 v128, v128
	v_sub_f32_e32 v112, v16, v234
	v_exp_f32_e32 v112, v112
	v_sub_f32_e32 v129, v65, v234
	v_exp_f32_e32 v129, v129
	v_sub_f32_e32 v113, v17, v234
	v_exp_f32_e32 v113, v113
	v_pk_mul_f32 v[18:19], v[18:19], v[162:163] op_sel_hi:[1,0]
	v_pk_mul_f32 v[20:21], v[20:21], v[162:163] op_sel_hi:[1,0]
	v_pk_mul_f32 v[22:23], v[22:23], v[162:163] op_sel_hi:[1,0]
	v_pk_mul_f32 v[24:25], v[24:25], v[162:163] op_sel_hi:[1,0]
	v_pk_mul_f32 v[26:27], v[26:27], v[162:163] op_sel_hi:[1,0]
	v_pk_mul_f32 v[28:29], v[28:29], v[162:163] op_sel_hi:[1,0]
	v_pk_mul_f32 v[30:31], v[30:31], v[162:163] op_sel_hi:[1,0]
	v_pk_mul_f32 v[32:33], v[32:33], v[162:163] op_sel_hi:[1,0]
	v_pk_mul_f32 v[34:35], v[34:35], v[162:163] op_sel_hi:[1,0]
	v_pk_mul_f32 v[36:37], v[36:37], v[162:163] op_sel_hi:[1,0]
	v_pk_mul_f32 v[38:39], v[38:39], v[162:163] op_sel_hi:[1,0]
	v_pk_mul_f32 v[40:41], v[40:41], v[162:163] op_sel_hi:[1,0]
	v_pk_mul_f32 v[42:43], v[42:43], v[162:163] op_sel_hi:[1,0]
	v_pk_mul_f32 v[44:45], v[44:45], v[162:163] op_sel_hi:[1,0]
	v_pk_mul_f32 v[46:47], v[46:47], v[162:163] op_sel_hi:[1,0]
	v_pk_mul_f32 v[48:49], v[48:49], v[162:163] op_sel_hi:[1,0]
	s_branch .Lm11_pv

; #define LAS __attribute__((address_space(3)))
; template <int MODE  > ...
;     ...
;         if (has_next) {
;             LAS bf16_t* kb = (LAS bf16_t*)(lds + A_KBUF) + (cur ^ 1) * 64 * KPITCH;
;             *(LAS u32x4*)(kb + skey * KPITCH + schunk * 8) = kreg;
;             if (NEEDV) { LAS bf16_t* vb = (LAS bf16_t*)(lds + A_VBUF) + (cur ^ 1) * 64 * VPITCH;
;                 *(LAS u32x4*)(vb + skey * VPITCH + schunk * 8) = vreg; }
;         }
;         __syncthreads();
;         if (!has_next) break;
;         j = jn; cur ^= 1;
.Lm11_w1:
	ds_write_b128 v166, v[130:133]
	ds_write_b128 v167, v[134:137] offset:18432
.Lm1_bot1:
	s_waitcnt lgkmcnt(0)
	s_barrier
	s_cmp_eq_u32 s20, 0
	s_cbranch_scc1 .Lm1_exit
	s_mov_b32 s68, s62
	s_mov_b32 s62, s4
	s_mov_b32 s20, s21
	s_branch .LBB0_248

; #define LAS __attribute__((address_space(3)))
; template <int MODE  > ...
;     ...
;         const bool has_next = rem != 0ull; int jn = 0;
;         if (has_next) { jn = 63 - __builtin_clzll(rem); rem &= ~(1ull << jn);
;             kreg = *(const u32x4*)(Kg + (size_t)(64 * jn + skey) * 128 + schunk * 8);
;             if (NEEDV) vreg = *(const u32x4*)(Vg + (size_t)(64 * jn + skey) * 128 + schunk * 8); }
;         const bool selbit = (MODE == 1) ? (((selmask >> j) & 1ull) != 0ull) : true;
;         bool active = true;
;         if (MODE == 1) active = __builtin_amdgcn_ballot_w64(selbit) != 0ull;
;         if (active) {
;             const LAS bf16_t* kb = (const LAS bf16_t*)(lds + A_KBUF) + cur * 64 * KPITCH;
;             constexpr int STEP = CMPM ? 16 : 1;
;             const int Bint = CMPM ? (1024 * j + 31 - t + 64 * h) : (64 * j - t + 4 * h);
;             const float sl = slope2 * (float)STEP;
;             const float mref = st.m; const bool fresh = !(mref > -1e28f);
;             const float mest = fresh ? 0.f : mref;
;             const float basef = selbit ? (slope2 * (float)Bint - mest) : -1e30f;
;             int ptype;
;             if (MODE == 1) ptype = (j == cblk) ? 1 : 0;
;             else if (MODE == 2) ptype = (j == cblk) ? 1 : ((j == cblk - 8) ? 2 : 0);
;             else ptype = (64 * j + 63 <= 4 * cblk - 2) ? 0 : 1;
;             f32x16 s0, s1;
;             { const float sl2 = sl + sl, sl3 = sl2 + sl;
; #pragma unroll
;               for (int g8 = 0; g8 < 4; ++g8) {
;                   const float b0 = __builtin_fmaf(sl, (float)(8 * g8), basef), b1 = __builtin_fmaf(sl, (float)(8 * g8 + 32), basef);
;                   s0[4 * g8] = b0; s0[4 * g8 + 1] = b0 + sl; s0[4 * g8 + 2] = b0 + sl2; s0[4 * g8 + 3] = b0 + sl3;
;                   s1[4 * g8] = b1; s1[4 * g8 + 1] = b1 + sl; s1[4 * g8 + 2] = b1 + sl2; s1[4 * g8 + 3] = b1 + sl3;
;               } }
;             if (ptype == 1) {
;                 const float thr = 0.5f * slope2 - mest;
; #pragma unroll
;                 for (int i = 0; i < 16; ++i) { s0[i] = (s0[i] < thr) ? s0[i] : -1e30f; s1[i] = (s1[i] < thr) ? s1[i] : -1e30f; }
;             } else if (ptype == 2) {
;                 const float thr = -511.5f * slope2 - mest;
; #pragma unroll
;                 for (int i = 0; i < 16; ++i) { s0[i] = (s0[i] > thr) ? s0[i] : -1e30f; s1[i] = (s1[i] > thr) ? s1[i] : -1e30f; }
;             }
.LBB0_268:
	s_mov_b32 s19, 0
	s_cmp_eq_u64 s[16:17], 0
	s_cbranch_scc1 .Lm20_noload
	s_flbit_i32_b64 s4, s[16:17]
	s_xor_b32 s4, s4, 63
	s_lshl_b64 vcc, 1, s4
	s_andn2_b64 s[16:17], s[16:17], vcc
	s_mov_b32 s19, 1
	v_lshl_add_u32 v34, s4, 6, v161
	v_ashrrev_i32_e32 v35, 31, v34
	v_lshlrev_b64 v[34:35], 8, v[34:35]
	v_lshl_add_u64 v[36:37], v[142:143], 0, v[34:35]
	v_lshl_add_u64 v[34:35], v[140:141], 0, v[34:35]
	global_load_dwordx4 v[130:133], v[36:37], off
	global_load_dwordx4 v[134:137], v[34:35], off
.Lm20_noload:
.Lm2_body0:
	ds_read_b128 v[66:69], v188
	ds_read_b128 v[70:73], v188 offset:4608
	ds_read_b128 v[74:77], v188 offset:32
	ds_read_b128 v[78:81], v188 offset:4640
	ds_read_b128 v[82:85], v188 offset:64
	ds_read_b128 v[86:89], v188 offset:4672
	ds_read_b128 v[90:93], v188 offset:96
	ds_read_b128 v[94:97], v188 offset:4704
	v_lshl_add_u32 v1, s20, 6, v167
	v_cvt_f32_i32_e32 v50, v1
	v_cmp_nlt_f32_e64 s[14:15], s71, v192
	s_cmp_eq_u32 s20, s23
	s_cselect_b32 s21, 2, 0
	s_cmp_lg_u32 s20, s83
	s_cselect_b32 s68, s21, 1
	s_cmp_eq_u32 s68, 0
	v_cndmask_b32_e64 v1, v192, 0, s[14:15]
	v_fma_f32 v62, v186, v50, -v1
	v_fma_f32 v34, 0, v186, v62
	v_fmamk_f32 v38, v186, 0x41000000, v62
	v_fmamk_f32 v42, v186, 0x41800000, v62
	v_fmamk_f32 v46, v186, 0x41c00000, v62
	v_fmamk_f32 v50, v186, 0x42000000, v62
	v_fmamk_f32 v54, v186, 0x42200000, v62
	v_fmamk_f32 v58, v186, 0x42400000, v62
	v_fmac_f32_e32 v62, 0x42600000, v186
	v_add_f32_e32 v35, v186, v34
	v_add_f32_e32 v36, v187, v34
	v_add_f32_e32 v37, v163, v34
	v_add_f32_e32 v39, v186, v38
	v_add_f32_e32 v40, v187, v38
	v_add_f32_e32 v41, v163, v38
	v_add_f32_e32 v43, v186, v42
	v_add_f32_e32 v44, v187, v42
	v_add_f32_e32 v45, v163, v42
	v_add_f32_e32 v47, v186, v46
	v_add_f32_e32 v48, v187, v46
	v_add_f32_e32 v49, v163, v46
	v_add_f32_e32 v51, v186, v50
	v_add_f32_e32 v52, v187, v50
	v_add_f32_e32 v53, v163, v50
	v_add_f32_e32 v55, v186, v54
	v_add_f32_e32 v56, v187, v54
	v_add_f32_e32 v57, v163, v54
	v_add_f32_e32 v59, v186, v58
	v_add_f32_e32 v60, v187, v58
	v_add_f32_e32 v61, v163, v58
	v_add_f32_e32 v63, v186, v62
	v_add_f32_e32 v64, v187, v62
	v_add_f32_e32 v65, v163, v62
	s_cbranch_scc1 .Lm20_qk
	s_cmp_eq_u32 s68, 1
	s_cbranch_scc1 .Lm20_edge1
	v_sub_f32_e32 v254, v162, v1
	v_cmp_gt_f32_e32 vcc, v34, v254
	s_nop 1
	v_cndmask_b32_e32 v34, v241, v34, vcc
	v_cmp_gt_f32_e32 vcc, v35, v254
	s_nop 1
	v_cndmask_b32_e32 v35, v241, v35, vcc
	v_cmp_gt_f32_e32 vcc, v36, v254
	s_nop 1
	v_cndmask_b32_e32 v36, v241, v36, vcc
	v_cmp_gt_f32_e32 vcc, v37, v254
	s_nop 1
	v_cndmask_b32_e32 v37, v241, v37, vcc
	v_cmp_gt_f32_e32 vcc, v38, v254
	s_nop 1
	v_cndmask_b32_e32 v38, v241, v38, vcc
	v_cmp_gt_f32_e32 vcc, v39, v254
	s_nop 1
	v_cndmask_b32_e32 v39, v241, v39, vcc
	v_cmp_gt_f32_e32 vcc, v40, v254
	s_nop 1
	v_cndmask_b32_e32 v40, v241, v40, vcc
	v_cmp_gt_f32_e32 vcc, v41, v254
	s_nop 1
	v_cndmask_b32_e32 v41, v241, v41, vcc
	v_cmp_gt_f32_e32 vcc, v42, v254
	s_nop 1
	v_cndmask_b32_e32 v42, v241, v42, vcc
	v_cmp_gt_f32_e32 vcc, v43, v254
	s_nop 1
	v_cndmask_b32_e32 v43, v241, v43, vcc
	v_cmp_gt_f32_e32 vcc, v44, v254
	s_nop 1
	v_cndmask_b32_e32 v44, v241, v44, vcc
	v_cmp_gt_f32_e32 vcc, v45, v254
	s_nop 1
	v_cndmask_b32_e32 v45, v241, v45, vcc
	v_cmp_gt_f32_e32 vcc, v46, v254
	s_nop 1
	v_cndmask_b32_e32 v46, v241, v46, vcc
	v_cmp_gt_f32_e32 vcc, v47, v254
	s_nop 1
	v_cndmask_b32_e32 v47, v241, v47, vcc
	v_cmp_gt_f32_e32 vcc, v48, v254
	s_nop 1
	v_cndmask_b32_e32 v48, v241, v48, vcc
	v_cmp_gt_f32_e32 vcc, v49, v254
	s_nop 1
	v_cndmask_b32_e32 v49, v241, v49, vcc
	v_cmp_gt_f32_e32 vcc, v50, v254
	s_nop 1
	v_cndmask_b32_e32 v50, v241, v50, vcc
	v_cmp_gt_f32_e32 vcc, v51, v254
	s_nop 1
	v_cndmask_b32_e32 v51, v241, v51, vcc
	v_cmp_gt_f32_e32 vcc, v52, v254
	s_nop 1
	v_cndmask_b32_e32 v52, v241, v52, vcc
	v_cmp_gt_f32_e32 vcc, v53, v254
	s_nop 1
	v_cndmask_b32_e32 v53, v241, v53, vcc
	v_cmp_gt_f32_e32 vcc, v54, v254
	s_nop 1
	v_cndmask_b32_e32 v54, v241, v54, vcc
	v_cmp_gt_f32_e32 vcc, v55, v254
	s_nop 1
	v_cndmask_b32_e32 v55, v241, v55, vcc
	v_cmp_gt_f32_e32 vcc, v56, v254
	s_nop 1
	v_cndmask_b32_e32 v56, v241, v56, vcc
	v_cmp_gt_f32_e32 vcc, v57, v254
	s_nop 1
	v_cndmask_b32_e32 v57, v241, v57, vcc
	v_cmp_gt_f32_e32 vcc, v58, v254
	s_nop 1
	v_cndmask_b32_e32 v58, v241, v58, vcc
	v_cmp_gt_f32_e32 vcc, v59, v254
	s_nop 1
	v_cndmask_b32_e32 v59, v241, v59, vcc
	v_cmp_gt_f32_e32 vcc, v60, v254
	s_nop 1
	v_cndmask_b32_e32 v60, v241, v60, vcc
	v_cmp_gt_f32_e32 vcc, v61, v254
	s_nop 1
	v_cndmask_b32_e32 v61, v241, v61, vcc
	v_cmp_gt_f32_e32 vcc, v62, v254
	s_nop 1
	v_cndmask_b32_e32 v62, v241, v62, vcc
	v_cmp_gt_f32_e32 vcc, v63, v254
	s_nop 1
	v_cndmask_b32_e32 v63, v241, v63, vcc
	v_cmp_gt_f32_e32 vcc, v64, v254
	s_nop 1
	v_cndmask_b32_e32 v64, v241, v64, vcc
	v_cmp_gt_f32_e32 vcc, v65, v254
	s_nop 1
	v_cndmask_b32_e32 v65, v241, v65, vcc
	s_branch .Lm20_qk
; template <int MODE  > ...
;     ...
;             } else if (ptype == 2) {
;                 const float thr = -511.5f * slope2 - mest;
; #pragma unroll
;                 for (int i = 0; i < 16; ++i) { s0[i] = (s0[i] > thr) ? s0[i] : -1e30f; s1[i] = (s1[i] > thr) ? s1[i] : -1e30f; }
;             }
.Lm20_edge1:
	v_sub_f32_e32 v254, v189, v1
	v_cmp_lt_f32_e32 vcc, v34, v254
	s_nop 1
	v_cndmask_b32_e32 v34, v241, v34, vcc
	v_cmp_lt_f32_e32 vcc, v35, v254
	s_nop 1
	v_cndmask_b32_e32 v35, v241, v35, vcc
	v_cmp_lt_f32_e32 vcc, v36, v254
	s_nop 1
	v_cndmask_b32_e32 v36, v241, v36, vcc
	v_cmp_lt_f32_e32 vcc, v37, v254
	s_nop 1
	v_cndmask_b32_e32 v37, v241, v37, vcc
	v_cmp_lt_f32_e32 vcc, v38, v254
	s_nop 1
	v_cndmask_b32_e32 v38, v241, v38, vcc
	v_cmp_lt_f32_e32 vcc, v39, v254
	s_nop 1
	v_cndmask_b32_e32 v39, v241, v39, vcc
	v_cmp_lt_f32_e32 vcc, v40, v254
	s_nop 1
	v_cndmask_b32_e32 v40, v241, v40, vcc
	v_cmp_lt_f32_e32 vcc, v41, v254
	s_nop 1
	v_cndmask_b32_e32 v41, v241, v41, vcc
	v_cmp_lt_f32_e32 vcc, v42, v254
	s_nop 1
	v_cndmask_b32_e32 v42, v241, v42, vcc
	v_cmp_lt_f32_e32 vcc, v43, v254
	s_nop 1
	v_cndmask_b32_e32 v43, v241, v43, vcc
	v_cmp_lt_f32_e32 vcc, v44, v254
	s_nop 1
	v_cndmask_b32_e32 v44, v241, v44, vcc
	v_cmp_lt_f32_e32 vcc, v45, v254
	s_nop 1
	v_cndmask_b32_e32 v45, v241, v45, vcc
	v_cmp_lt_f32_e32 vcc, v46, v254
	s_nop 1
	v_cndmask_b32_e32 v46, v241, v46, vcc
	v_cmp_lt_f32_e32 vcc, v47, v254
	s_nop 1
	v_cndmask_b32_e32 v47, v241, v47, vcc
	v_cmp_lt_f32_e32 vcc, v48, v254
	s_nop 1
	v_cndmask_b32_e32 v48, v241, v48, vcc
	v_cmp_lt_f32_e32 vcc, v49, v254
	s_nop 1
	v_cndmask_b32_e32 v49, v241, v49, vcc
	v_cmp_lt_f32_e32 vcc, v50, v254
	s_nop 1
	v_cndmask_b32_e32 v50, v241, v50, vcc
	v_cmp_lt_f32_e32 vcc, v51, v254
	s_nop 1
	v_cndmask_b32_e32 v51, v241, v51, vcc
	v_cmp_lt_f32_e32 vcc, v52, v254
	s_nop 1
	v_cndmask_b32_e32 v52, v241, v52, vcc
	v_cmp_lt_f32_e32 vcc, v53, v254
	s_nop 1
	v_cndmask_b32_e32 v53, v241, v53, vcc
	v_cmp_lt_f32_e32 vcc, v54, v254
	s_nop 1
	v_cndmask_b32_e32 v54, v241, v54, vcc
	v_cmp_lt_f32_e32 vcc, v55, v254
	s_nop 1
	v_cndmask_b32_e32 v55, v241, v55, vcc
	v_cmp_lt_f32_e32 vcc, v56, v254
	s_nop 1
	v_cndmask_b32_e32 v56, v241, v56, vcc
	v_cmp_lt_f32_e32 vcc, v57, v254
	s_nop 1
	v_cndmask_b32_e32 v57, v241, v57, vcc
	v_cmp_lt_f32_e32 vcc, v58, v254
	s_nop 1
	v_cndmask_b32_e32 v58, v241, v58, vcc
	v_cmp_lt_f32_e32 vcc, v59, v254
	s_nop 1
	v_cndmask_b32_e32 v59, v241, v59, vcc
	v_cmp_lt_f32_e32 vcc, v60, v254
	s_nop 1
	v_cndmask_b32_e32 v60, v241, v60, vcc
	v_cmp_lt_f32_e32 vcc, v61, v254
	s_nop 1
	v_cndmask_b32_e32 v61, v241, v61, vcc
	v_cmp_lt_f32_e32 vcc, v62, v254
	s_nop 1
	v_cndmask_b32_e32 v62, v241, v62, vcc
	v_cmp_lt_f32_e32 vcc, v63, v254
	s_nop 1
	v_cndmask_b32_e32 v63, v241, v63, vcc
	v_cmp_lt_f32_e32 vcc, v64, v254
	s_nop 1
	v_cndmask_b32_e32 v64, v241, v64, vcc
	v_cmp_lt_f32_e32 vcc, v65, v254
	s_nop 1
	v_cndmask_b32_e32 v65, v241, v65, vcc
; #define LAS __attribute__((address_space(3)))
; __device__ __forceinline__ float shflx(float v, int mask, int lane) { return __builtin_bit_cast(float, __builtin_amdgcn_ds_bpermute(((lane ^ mask) & 63) << 2, __builtin_bit_cast(int, v))); }
; template <int MODE  > ...
;     ...
;             for (int kk = 0; kk < 4; ++kk) {
;                 const bf16x8 k0 = *(const LAS bf16x8*)(kb + col * KPITCH + kk * 16 + h * 8);
;                 const bf16x8 k1 = *(const LAS bf16x8*)(kb + (32 + col) * KPITCH + kk * 16 + h * 8);
;                 s0 = __builtin_amdgcn_mfma_f32_32x32x16_bf16(k0, qf[kk], s0, 0, 0, 0);
;                 s1 = __builtin_amdgcn_mfma_f32_32x32x16_bf16(k1, qf[kk], s1, 0, 0, 0);
;             }
;             if (MODE != 3) {
;                 float mx = fmaxf(s0[0], s1[0]);
; #pragma unroll
;                 for (int i = 1; i < 16; ++i) mx = fmaxf(mx, fmaxf(s0[i], s1[i]));
;                 mx = fmaxf(mx, shflx(mx, 32, lane));
;                 float alpha = 1.f;
;                 if (__builtin_amdgcn_ballot_w64(fresh || mx > 0.f) != 0ull) {
;                     const float moldr = fresh ? -1e29f : 0.f, mnewr = fmaxf(moldr, mx);
;                     alpha = __builtin_amdgcn_exp2f(moldr - mnewr);
;                     st.m = mest + mnewr;
; #pragma unroll
;                     for (int i = 0; i < 16; ++i) { s0[i] = __builtin_amdgcn_exp2f(s0[i] - mnewr); s1[i] = __builtin_amdgcn_exp2f(s1[i] - mnewr); }
;                     st.o0 *= alpha; st.o1 *= alpha;
.Lm20_qk:
	s_waitcnt lgkmcnt(6)
	v_mfma_f32_32x32x16_bf16 v[34:49], v[66:69], v[144:147], v[34:49]
	v_mfma_f32_32x32x16_bf16 v[50:65], v[70:73], v[144:147], v[50:65]
	s_waitcnt lgkmcnt(4)
	v_mfma_f32_32x32x16_bf16 v[34:49], v[74:77], v[148:151], v[34:49]
	v_mfma_f32_32x32x16_bf16 v[50:65], v[78:81], v[148:151], v[50:65]
	s_waitcnt lgkmcnt(2)
	v_mfma_f32_32x32x16_bf16 v[34:49], v[82:85], v[152:155], v[34:49]
	v_mfma_f32_32x32x16_bf16 v[50:65], v[86:89], v[152:155], v[50:65]
	s_waitcnt lgkmcnt(0)
	v_mfma_f32_32x32x16_bf16 v[34:49], v[90:93], v[156:159], v[34:49]
	v_mfma_f32_32x32x16_bf16 v[50:65], v[94:97], v[156:159], v[50:65]
	ds_read_b64_tr_b16 v[66:67], v191 offset:18432
	ds_read_b64_tr_b16 v[68:69], v191 offset:19968
	ds_read_b64_tr_b16 v[70:71], v191 offset:18496
	ds_read_b64_tr_b16 v[72:73], v191 offset:20032
	ds_read_b64_tr_b16 v[74:75], v191 offset:21504
	ds_read_b64_tr_b16 v[76:77], v191 offset:23040
	ds_read_b64_tr_b16 v[78:79], v191 offset:21568
	ds_read_b64_tr_b16 v[80:81], v191 offset:23104
	s_nop 3
	v_max3_f32 v234, v34, v35, v36
	v_max3_f32 v234, v234, v37, v38
	v_max3_f32 v234, v234, v39, v40
	v_max3_f32 v234, v234, v41, v42
	v_max3_f32 v234, v234, v43, v44
	v_max3_f32 v234, v234, v45, v46
	v_max3_f32 v234, v234, v47, v48
	v_max3_f32 v235, v50, v51, v52
	v_max3_f32 v235, v235, v53, v54
	v_max3_f32 v235, v235, v55, v56
	v_max3_f32 v235, v235, v57, v58
	v_max3_f32 v235, v235, v59, v60
	v_max3_f32 v235, v235, v61, v62
	v_max3_f32 v235, v235, v63, v64
	v_max3_f32 v234, v234, v49, v65
	v_max_f32_e32 v234, v234, v235
	v_mov_b32_e32 v235, v234
	s_waitcnt lgkmcnt(7)
	ds_read_b64_tr_b16 v[82:83], v191 offset:24576
	ds_read_b64_tr_b16 v[84:85], v191 offset:26112
	ds_read_b64_tr_b16 v[86:87], v191 offset:24640
	ds_read_b64_tr_b16 v[88:89], v191 offset:26176
	ds_read_b64_tr_b16 v[90:91], v191 offset:27648
	ds_read_b64_tr_b16 v[92:93], v191 offset:29184
	ds_read_b64_tr_b16 v[94:95], v191 offset:27712
	ds_read_b64_tr_b16 v[96:97], v191 offset:29248
	v_permlane32_swap_b32_e32 v235, v234
	v_max_f32_e32 v234, v234, v235
	v_cmp_lt_f32_e32 vcc, 0, v234
	s_or_b64 vcc, s[14:15], vcc
	s_cbranch_vccz .Lm20_norescale
	v_cndmask_b32_e64 v235, 0, v242, s[14:15]
	v_max_f32_e32 v234, v235, v234
	v_sub_f32_e32 v235, v235, v234
	v_exp_f32_e32 v160, v235
	v_add_f32_e32 v192, v1, v234
	v_sub_f32_e32 v114, v34, v234
	v_exp_f32_e32 v114, v114
	v_sub_f32_e32 v98, v50, v234
	v_exp_f32_e32 v98, v98
	v_sub_f32_e32 v115, v35, v234
	v_exp_f32_e32 v115, v115
	v_sub_f32_e32 v99, v51, v234
	v_exp_f32_e32 v99, v99
	v_sub_f32_e32 v116, v36, v234
	v_exp_f32_e32 v116, v116
	v_sub_f32_e32 v100, v52, v234
	v_exp_f32_e32 v100, v100
	v_sub_f32_e32 v117, v37, v234
	v_exp_f32_e32 v117, v117
	v_sub_f32_e32 v101, v53, v234
	v_exp_f32_e32 v101, v101
	v_sub_f32_e32 v118, v38, v234
	v_exp_f32_e32 v118, v118
	v_sub_f32_e32 v102, v54, v234
	v_exp_f32_e32 v102, v102
	v_sub_f32_e32 v119, v39, v234
	v_exp_f32_e32 v119, v119
	v_sub_f32_e32 v103, v55, v234
	v_exp_f32_e32 v103, v103
	v_sub_f32_e32 v120, v40, v234
	v_exp_f32_e32 v120, v120
	v_sub_f32_e32 v104, v56, v234
	v_exp_f32_e32 v104, v104
	v_sub_f32_e32 v121, v41, v234
	v_exp_f32_e32 v121, v121
	v_sub_f32_e32 v105, v57, v234
	v_exp_f32_e32 v105, v105
	v_sub_f32_e32 v122, v42, v234
	v_exp_f32_e32 v122, v122
	v_sub_f32_e32 v106, v58, v234
	v_exp_f32_e32 v106, v106
	v_sub_f32_e32 v123, v43, v234
	v_exp_f32_e32 v123, v123
	v_sub_f32_e32 v107, v59, v234
	v_exp_f32_e32 v107, v107
	v_sub_f32_e32 v124, v44, v234
	v_exp_f32_e32 v124, v124
	v_sub_f32_e32 v108, v60, v234
	v_exp_f32_e32 v108, v108
	v_sub_f32_e32 v125, v45, v234
	v_exp_f32_e32 v125, v125
	v_sub_f32_e32 v109, v61, v234
	v_exp_f32_e32 v109, v109
	v_sub_f32_e32 v126, v46, v234
	v_exp_f32_e32 v126, v126
	v_sub_f32_e32 v110, v62, v234
	v_exp_f32_e32 v110, v110
	v_sub_f32_e32 v127, v47, v234
	v_exp_f32_e32 v127, v127
	v_sub_f32_e32 v111, v63, v234
	v_exp_f32_e32 v111, v111
	v_sub_f32_e32 v128, v48, v234
	v_exp_f32_e32 v128, v128
	v_sub_f32_e32 v112, v64, v234
	v_exp_f32_e32 v112, v112
	v_sub_f32_e32 v129, v49, v234
	v_exp_f32_e32 v129, v129
	v_sub_f32_e32 v113, v65, v234
	v_exp_f32_e32 v113, v113
	v_pk_mul_f32 v[18:19], v[18:19], v[160:161] op_sel_hi:[1,0]
	v_pk_mul_f32 v[20:21], v[20:21], v[160:161] op_sel_hi:[1,0]
	v_pk_mul_f32 v[22:23], v[22:23], v[160:161] op_sel_hi:[1,0]
	v_pk_mul_f32 v[24:25], v[24:25], v[160:161] op_sel_hi:[1,0]
	v_pk_mul_f32 v[26:27], v[26:27], v[160:161] op_sel_hi:[1,0]
	v_pk_mul_f32 v[28:29], v[28:29], v[160:161] op_sel_hi:[1,0]
	v_pk_mul_f32 v[30:31], v[30:31], v[160:161] op_sel_hi:[1,0]
	v_pk_mul_f32 v[32:33], v[32:33], v[160:161] op_sel_hi:[1,0]
	v_pk_mul_f32 v[2:3], v[2:3], v[160:161] op_sel_hi:[1,0]
	v_pk_mul_f32 v[4:5], v[4:5], v[160:161] op_sel_hi:[1,0]
	v_pk_mul_f32 v[6:7], v[6:7], v[160:161] op_sel_hi:[1,0]
	v_pk_mul_f32 v[8:9], v[8:9], v[160:161] op_sel_hi:[1,0]
	v_pk_mul_f32 v[10:11], v[10:11], v[160:161] op_sel_hi:[1,0]
	v_pk_mul_f32 v[12:13], v[12:13], v[160:161] op_sel_hi:[1,0]
	v_pk_mul_f32 v[14:15], v[14:15], v[160:161] op_sel_hi:[1,0]
	v_pk_mul_f32 v[16:17], v[16:17], v[160:161] op_sel_hi:[1,0]
	s_branch .Lm20_pv

; #define LAS __attribute__((address_space(3)))
; template <int MODE  > ...
;     ...
;         if (has_next) {
;             LAS bf16_t* kb = (LAS bf16_t*)(lds + A_KBUF) + (cur ^ 1) * 64 * KPITCH;
;             *(LAS u32x4*)(kb + skey * KPITCH + schunk * 8) = kreg;
;             if (NEEDV) { LAS bf16_t* vb = (LAS bf16_t*)(lds + A_VBUF) + (cur ^ 1) * 64 * VPITCH;
;                 *(LAS u32x4*)(vb + skey * VPITCH + schunk * 8) = vreg; }
;         }
;         __syncthreads();
.Lm2_stage0:
	s_cmp_eq_u32 s18, 0
	s_cbranch_scc1 .Lm2_bot0
	s_cmp_eq_u32 s19, 0
	s_cbranch_scc1 .Lm20_w0
	s_waitcnt vmcnt(2)
	s_branch .Lm20_w1

; #define LAS __attribute__((address_space(3)))
; template <int MODE  > ...
;     ...
;         const bool has_next = rem != 0ull; int jn = 0;
;         if (has_next) { jn = 63 - __builtin_clzll(rem); rem &= ~(1ull << jn);
;             kreg = *(const u32x4*)(Kg + (size_t)(64 * jn + skey) * 128 + schunk * 8);
;             if (NEEDV) vreg = *(const u32x4*)(Vg + (size_t)(64 * jn + skey) * 128 + schunk * 8); }
;         const bool selbit = (MODE == 1) ? (((selmask >> j) & 1ull) != 0ull) : true;
;         bool active = true;
;         if (MODE == 1) active = __builtin_amdgcn_ballot_w64(selbit) != 0ull;
;         if (active) {
;             const LAS bf16_t* kb = (const LAS bf16_t*)(lds + A_KBUF) + cur * 64 * KPITCH;
;             constexpr int STEP = CMPM ? 16 : 1;
;             const int Bint = CMPM ? (1024 * j + 31 - t + 64 * h) : (64 * j - t + 4 * h);
;             const float sl = slope2 * (float)STEP;
;             const float mref = st.m; const bool fresh = !(mref > -1e28f);
;             const float mest = fresh ? 0.f : mref;
;             const float basef = selbit ? (slope2 * (float)Bint - mest) : -1e30f;
;             int ptype;
;             if (MODE == 1) ptype = (j == cblk) ? 1 : 0;
;             else if (MODE == 2) ptype = (j == cblk) ? 1 : ((j == cblk - 8) ? 2 : 0);
;             else ptype = (64 * j + 63 <= 4 * cblk - 2) ? 0 : 1;
;             f32x16 s0, s1;
;             { const float sl2 = sl + sl, sl3 = sl2 + sl;
; #pragma unroll
;               for (int g8 = 0; g8 < 4; ++g8) {
;                   const float b0 = __builtin_fmaf(sl, (float)(8 * g8), basef), b1 = __builtin_fmaf(sl, (float)(8 * g8 + 32), basef);
;                   s0[4 * g8] = b0; s0[4 * g8 + 1] = b0 + sl; s0[4 * g8 + 2] = b0 + sl2; s0[4 * g8 + 3] = b0 + sl3;
;                   s1[4 * g8] = b1; s1[4 * g8 + 1] = b1 + sl; s1[4 * g8 + 2] = b1 + sl2; s1[4 * g8 + 3] = b1 + sl3;
;               } }
;             if (ptype == 1) {
;     ...
;         if (has_next) {
;             LAS bf16_t* kb = (LAS bf16_t*)(lds + A_KBUF) + (cur ^ 1) * 64 * KPITCH;
;             *(LAS u32x4*)(kb + skey * KPITCH + schunk * 8) = kreg;
;             if (NEEDV) { LAS bf16_t* vb = (LAS bf16_t*)(lds + A_VBUF) + (cur ^ 1) * 64 * VPITCH;
;                 *(LAS u32x4*)(vb + skey * VPITCH + schunk * 8) = vreg; }
;         }
;         __syncthreads();
;         if (!has_next) break;
;         j = jn; cur ^= 1;
;     }
.Lm20_w1:
	ds_write_b128 v165, v[226:229] offset:9216
	ds_write_b128 v166, v[230:233] offset:30720
.Lm2_bot0:
	s_waitcnt lgkmcnt(0)
	s_barrier
	s_cmp_eq_u32 s18, 0
	s_cbranch_scc1 .Lm2_exit
	s_mov_b32 s20, s62
	s_mov_b32 s62, s4
	s_mov_b32 s18, s19
.Lm2_loop1:
	s_mov_b32 s19, 0
	s_cmp_eq_u64 s[16:17], 0
	s_cbranch_scc1 .Lm21_noload
	s_flbit_i32_b64 s4, s[16:17]
	s_xor_b32 s4, s4, 63
	s_lshl_b64 vcc, 1, s4
	s_andn2_b64 s[16:17], s[16:17], vcc
	s_mov_b32 s19, 1
	v_lshl_add_u32 v34, s4, 6, v161
	v_ashrrev_i32_e32 v35, 31, v34
	v_lshlrev_b64 v[34:35], 8, v[34:35]
	v_lshl_add_u64 v[36:37], v[142:143], 0, v[34:35]
	v_lshl_add_u64 v[34:35], v[140:141], 0, v[34:35]
	global_load_dwordx4 v[226:229], v[36:37], off
	global_load_dwordx4 v[230:233], v[34:35], off
.Lm21_noload:
.Lm2_body1:
	ds_read_b128 v[66:69], v188 offset:9216
	ds_read_b128 v[70:73], v188 offset:13824
	ds_read_b128 v[74:77], v188 offset:9248
	ds_read_b128 v[78:81], v188 offset:13856
	ds_read_b128 v[82:85], v188 offset:9280
	ds_read_b128 v[86:89], v188 offset:13888
	ds_read_b128 v[90:93], v188 offset:9312
	ds_read_b128 v[94:97], v188 offset:13920
	v_lshl_add_u32 v1, s20, 6, v167
	v_cvt_f32_i32_e32 v50, v1
	v_cmp_nlt_f32_e64 s[14:15], s71, v192
	s_cmp_eq_u32 s20, s23
	s_cselect_b32 s21, 2, 0
	s_cmp_lg_u32 s20, s83
	s_cselect_b32 s68, s21, 1
	s_cmp_eq_u32 s68, 0
	v_cndmask_b32_e64 v1, v192, 0, s[14:15]
	v_fma_f32 v62, v186, v50, -v1
	v_fma_f32 v34, 0, v186, v62
	v_fmamk_f32 v38, v186, 0x41000000, v62
	v_fmamk_f32 v42, v186, 0x41800000, v62
	v_fmamk_f32 v46, v186, 0x41c00000, v62
	v_fmamk_f32 v50, v186, 0x42000000, v62
	v_fmamk_f32 v54, v186, 0x42200000, v62
	v_fmamk_f32 v58, v186, 0x42400000, v62
	v_fmac_f32_e32 v62, 0x42600000, v186
	v_add_f32_e32 v35, v186, v34
	v_add_f32_e32 v36, v187, v34
	v_add_f32_e32 v37, v163, v34
	v_add_f32_e32 v39, v186, v38
	v_add_f32_e32 v40, v187, v38
	v_add_f32_e32 v41, v163, v38
	v_add_f32_e32 v43, v186, v42
	v_add_f32_e32 v44, v187, v42
	v_add_f32_e32 v45, v163, v42
	v_add_f32_e32 v47, v186, v46
	v_add_f32_e32 v48, v187, v46
	v_add_f32_e32 v49, v163, v46
	v_add_f32_e32 v51, v186, v50
	v_add_f32_e32 v52, v187, v50
	v_add_f32_e32 v53, v163, v50
	v_add_f32_e32 v55, v186, v54
	v_add_f32_e32 v56, v187, v54
	v_add_f32_e32 v57, v163, v54
	v_add_f32_e32 v59, v186, v58
	v_add_f32_e32 v60, v187, v58
	v_add_f32_e32 v61, v163, v58
	v_add_f32_e32 v63, v186, v62
	v_add_f32_e32 v64, v187, v62
	v_add_f32_e32 v65, v163, v62
	s_cbranch_scc1 .Lm21_qk
	s_cmp_eq_u32 s68, 1
	s_cbranch_scc1 .Lm21_edge1
	v_sub_f32_e32 v254, v162, v1
	v_cmp_gt_f32_e32 vcc, v34, v254
	s_nop 1
	v_cndmask_b32_e32 v34, v241, v34, vcc
	v_cmp_gt_f32_e32 vcc, v35, v254
	s_nop 1
	v_cndmask_b32_e32 v35, v241, v35, vcc
	v_cmp_gt_f32_e32 vcc, v36, v254
	s_nop 1
	v_cndmask_b32_e32 v36, v241, v36, vcc
	v_cmp_gt_f32_e32 vcc, v37, v254
	s_nop 1
	v_cndmask_b32_e32 v37, v241, v37, vcc
	v_cmp_gt_f32_e32 vcc, v38, v254
	s_nop 1
	v_cndmask_b32_e32 v38, v241, v38, vcc
	v_cmp_gt_f32_e32 vcc, v39, v254
	s_nop 1
	v_cndmask_b32_e32 v39, v241, v39, vcc
	v_cmp_gt_f32_e32 vcc, v40, v254
	s_nop 1
	v_cndmask_b32_e32 v40, v241, v40, vcc
	v_cmp_gt_f32_e32 vcc, v41, v254
	s_nop 1
	v_cndmask_b32_e32 v41, v241, v41, vcc
	v_cmp_gt_f32_e32 vcc, v42, v254
	s_nop 1
	v_cndmask_b32_e32 v42, v241, v42, vcc
	v_cmp_gt_f32_e32 vcc, v43, v254
	s_nop 1
	v_cndmask_b32_e32 v43, v241, v43, vcc
	v_cmp_gt_f32_e32 vcc, v44, v254
	s_nop 1
	v_cndmask_b32_e32 v44, v241, v44, vcc
	v_cmp_gt_f32_e32 vcc, v45, v254
	s_nop 1
	v_cndmask_b32_e32 v45, v241, v45, vcc
	v_cmp_gt_f32_e32 vcc, v46, v254
	s_nop 1
	v_cndmask_b32_e32 v46, v241, v46, vcc
	v_cmp_gt_f32_e32 vcc, v47, v254
	s_nop 1
	v_cndmask_b32_e32 v47, v241, v47, vcc
	v_cmp_gt_f32_e32 vcc, v48, v254
	s_nop 1
	v_cndmask_b32_e32 v48, v241, v48, vcc
	v_cmp_gt_f32_e32 vcc, v49, v254
	s_nop 1
	v_cndmask_b32_e32 v49, v241, v49, vcc
	v_cmp_gt_f32_e32 vcc, v50, v254
	s_nop 1
	v_cndmask_b32_e32 v50, v241, v50, vcc
	v_cmp_gt_f32_e32 vcc, v51, v254
	s_nop 1
	v_cndmask_b32_e32 v51, v241, v51, vcc
	v_cmp_gt_f32_e32 vcc, v52, v254
	s_nop 1
	v_cndmask_b32_e32 v52, v241, v52, vcc
	v_cmp_gt_f32_e32 vcc, v53, v254
	s_nop 1
	v_cndmask_b32_e32 v53, v241, v53, vcc
	v_cmp_gt_f32_e32 vcc, v54, v254
	s_nop 1
	v_cndmask_b32_e32 v54, v241, v54, vcc
	v_cmp_gt_f32_e32 vcc, v55, v254
	s_nop 1
	v_cndmask_b32_e32 v55, v241, v55, vcc
	v_cmp_gt_f32_e32 vcc, v56, v254
	s_nop 1
	v_cndmask_b32_e32 v56, v241, v56, vcc
	v_cmp_gt_f32_e32 vcc, v57, v254
	s_nop 1
	v_cndmask_b32_e32 v57, v241, v57, vcc
	v_cmp_gt_f32_e32 vcc, v58, v254
	s_nop 1
	v_cndmask_b32_e32 v58, v241, v58, vcc
	v_cmp_gt_f32_e32 vcc, v59, v254
	s_nop 1
	v_cndmask_b32_e32 v59, v241, v59, vcc
	v_cmp_gt_f32_e32 vcc, v60, v254
	s_nop 1
	v_cndmask_b32_e32 v60, v241, v60, vcc
	v_cmp_gt_f32_e32 vcc, v61, v254
	s_nop 1
	v_cndmask_b32_e32 v61, v241, v61, vcc
	v_cmp_gt_f32_e32 vcc, v62, v254
	s_nop 1
	v_cndmask_b32_e32 v62, v241, v62, vcc
	v_cmp_gt_f32_e32 vcc, v63, v254
	s_nop 1
	v_cndmask_b32_e32 v63, v241, v63, vcc
	v_cmp_gt_f32_e32 vcc, v64, v254
	s_nop 1
	v_cndmask_b32_e32 v64, v241, v64, vcc
	v_cmp_gt_f32_e32 vcc, v65, v254
	s_nop 1
	v_cndmask_b32_e32 v65, v241, v65, vcc
	s_branch .Lm21_qk

; #define LAS __attribute__((address_space(3)))
; __device__ __forceinline__ float shflx(float v, int mask, int lane) { return __builtin_bit_cast(float, __builtin_amdgcn_ds_bpermute(((lane ^ mask) & 63) << 2, __builtin_bit_cast(int, v))); }
; template <int MODE  > ...
;     ...
;             for (int kk = 0; kk < 4; ++kk) {
;                 const bf16x8 k0 = *(const LAS bf16x8*)(kb + col * KPITCH + kk * 16 + h * 8);
;                 const bf16x8 k1 = *(const LAS bf16x8*)(kb + (32 + col) * KPITCH + kk * 16 + h * 8);
;                 s0 = __builtin_amdgcn_mfma_f32_32x32x16_bf16(k0, qf[kk], s0, 0, 0, 0);
;                 s1 = __builtin_amdgcn_mfma_f32_32x32x16_bf16(k1, qf[kk], s1, 0, 0, 0);
;             }
;             if (MODE != 3) {
;                 float mx = fmaxf(s0[0], s1[0]);
; #pragma unroll
;                 for (int i = 1; i < 16; ++i) mx = fmaxf(mx, fmaxf(s0[i], s1[i]));
;                 mx = fmaxf(mx, shflx(mx, 32, lane));
;                 float alpha = 1.f;
;                 if (__builtin_amdgcn_ballot_w64(fresh || mx > 0.f) != 0ull) {
;                     const float moldr = fresh ? -1e29f : 0.f, mnewr = fmaxf(moldr, mx);
;                     alpha = __builtin_amdgcn_exp2f(moldr - mnewr);
;                     st.m = mest + mnewr;
; #pragma unroll
;                     for (int i = 0; i < 16; ++i) { s0[i] = __builtin_amdgcn_exp2f(s0[i] - mnewr); s1[i] = __builtin_amdgcn_exp2f(s1[i] - mnewr); }
;                     st.o0 *= alpha; st.o1 *= alpha;
.Lm21_qk:
	s_waitcnt lgkmcnt(6)
	v_mfma_f32_32x32x16_bf16 v[34:49], v[66:69], v[144:147], v[34:49]
	v_mfma_f32_32x32x16_bf16 v[50:65], v[70:73], v[144:147], v[50:65]
	s_waitcnt lgkmcnt(4)
	v_mfma_f32_32x32x16_bf16 v[34:49], v[74:77], v[148:151], v[34:49]
	v_mfma_f32_32x32x16_bf16 v[50:65], v[78:81], v[148:151], v[50:65]
	s_waitcnt lgkmcnt(2)
	v_mfma_f32_32x32x16_bf16 v[34:49], v[82:85], v[152:155], v[34:49]
	v_mfma_f32_32x32x16_bf16 v[50:65], v[86:89], v[152:155], v[50:65]
	s_waitcnt lgkmcnt(0)
	v_mfma_f32_32x32x16_bf16 v[34:49], v[90:93], v[156:159], v[34:49]
	v_mfma_f32_32x32x16_bf16 v[50:65], v[94:97], v[156:159], v[50:65]
	ds_read_b64_tr_b16 v[66:67], v191 offset:30720
	ds_read_b64_tr_b16 v[68:69], v191 offset:32256
	ds_read_b64_tr_b16 v[70:71], v191 offset:30784
	ds_read_b64_tr_b16 v[72:73], v191 offset:32320
	ds_read_b64_tr_b16 v[74:75], v191 offset:33792
	ds_read_b64_tr_b16 v[76:77], v191 offset:35328
	ds_read_b64_tr_b16 v[78:79], v191 offset:33856
	ds_read_b64_tr_b16 v[80:81], v191 offset:35392
	s_nop 3
	v_max3_f32 v234, v34, v35, v36
	v_max3_f32 v234, v234, v37, v38
	v_max3_f32 v234, v234, v39, v40
	v_max3_f32 v234, v234, v41, v42
	v_max3_f32 v234, v234, v43, v44
	v_max3_f32 v234, v234, v45, v46
	v_max3_f32 v234, v234, v47, v48
	v_max3_f32 v235, v50, v51, v52
	v_max3_f32 v235, v235, v53, v54
	v_max3_f32 v235, v235, v55, v56
	v_max3_f32 v235, v235, v57, v58
	v_max3_f32 v235, v235, v59, v60
	v_max3_f32 v235, v235, v61, v62
	v_max3_f32 v235, v235, v63, v64
	v_max3_f32 v234, v234, v49, v65
	v_max_f32_e32 v234, v234, v235
	v_mov_b32_e32 v235, v234
	s_waitcnt lgkmcnt(7)
	ds_read_b64_tr_b16 v[82:83], v191 offset:36864
	ds_read_b64_tr_b16 v[84:85], v191 offset:38400
	ds_read_b64_tr_b16 v[86:87], v191 offset:36928
	ds_read_b64_tr_b16 v[88:89], v191 offset:38464
	ds_read_b64_tr_b16 v[90:91], v191 offset:39936
	ds_read_b64_tr_b16 v[92:93], v191 offset:41472
	ds_read_b64_tr_b16 v[94:95], v191 offset:40000
	ds_read_b64_tr_b16 v[96:97], v191 offset:41536
	v_permlane32_swap_b32_e32 v235, v234
	v_max_f32_e32 v234, v234, v235
	v_cmp_lt_f32_e32 vcc, 0, v234
	s_or_b64 vcc, s[14:15], vcc
	s_cbranch_vccz .Lm21_norescale
	v_cndmask_b32_e64 v235, 0, v242, s[14:15]
	v_max_f32_e32 v234, v235, v234
	v_sub_f32_e32 v235, v235, v234
	v_exp_f32_e32 v160, v235
	v_add_f32_e32 v192, v1, v234
	v_sub_f32_e32 v114, v34, v234
	v_exp_f32_e32 v114, v114
	v_sub_f32_e32 v98, v50, v234
	v_exp_f32_e32 v98, v98
	v_sub_f32_e32 v115, v35, v234
	v_exp_f32_e32 v115, v115
	v_sub_f32_e32 v99, v51, v234
	v_exp_f32_e32 v99, v99
	v_sub_f32_e32 v116, v36, v234
	v_exp_f32_e32 v116, v116
	v_sub_f32_e32 v100, v52, v234
	v_exp_f32_e32 v100, v100
	v_sub_f32_e32 v117, v37, v234
	v_exp_f32_e32 v117, v117
	v_sub_f32_e32 v101, v53, v234
	v_exp_f32_e32 v101, v101
	v_sub_f32_e32 v118, v38, v234
	v_exp_f32_e32 v118, v118
	v_sub_f32_e32 v102, v54, v234
	v_exp_f32_e32 v102, v102
	v_sub_f32_e32 v119, v39, v234
	v_exp_f32_e32 v119, v119
	v_sub_f32_e32 v103, v55, v234
	v_exp_f32_e32 v103, v103
	v_sub_f32_e32 v120, v40, v234
	v_exp_f32_e32 v120, v120
	v_sub_f32_e32 v104, v56, v234
	v_exp_f32_e32 v104, v104
	v_sub_f32_e32 v121, v41, v234
	v_exp_f32_e32 v121, v121
	v_sub_f32_e32 v105, v57, v234
	v_exp_f32_e32 v105, v105
	v_sub_f32_e32 v122, v42, v234
	v_exp_f32_e32 v122, v122
	v_sub_f32_e32 v106, v58, v234
	v_exp_f32_e32 v106, v106
	v_sub_f32_e32 v123, v43, v234
	v_exp_f32_e32 v123, v123
	v_sub_f32_e32 v107, v59, v234
	v_exp_f32_e32 v107, v107
	v_sub_f32_e32 v124, v44, v234
	v_exp_f32_e32 v124, v124
	v_sub_f32_e32 v108, v60, v234
	v_exp_f32_e32 v108, v108
	v_sub_f32_e32 v125, v45, v234
	v_exp_f32_e32 v125, v125
	v_sub_f32_e32 v109, v61, v234
	v_exp_f32_e32 v109, v109
	v_sub_f32_e32 v126, v46, v234
	v_exp_f32_e32 v126, v126
	v_sub_f32_e32 v110, v62, v234
	v_exp_f32_e32 v110, v110
	v_sub_f32_e32 v127, v47, v234
	v_exp_f32_e32 v127, v127
	v_sub_f32_e32 v111, v63, v234
	v_exp_f32_e32 v111, v111
	v_sub_f32_e32 v128, v48, v234
	v_exp_f32_e32 v128, v128
	v_sub_f32_e32 v112, v64, v234
	v_exp_f32_e32 v112, v112
	v_sub_f32_e32 v129, v49, v234
	v_exp_f32_e32 v129, v129
	v_sub_f32_e32 v113, v65, v234
	v_exp_f32_e32 v113, v113
	v_pk_mul_f32 v[18:19], v[18:19], v[160:161] op_sel_hi:[1,0]
	v_pk_mul_f32 v[20:21], v[20:21], v[160:161] op_sel_hi:[1,0]
	v_pk_mul_f32 v[22:23], v[22:23], v[160:161] op_sel_hi:[1,0]
	v_pk_mul_f32 v[24:25], v[24:25], v[160:161] op_sel_hi:[1,0]
	v_pk_mul_f32 v[26:27], v[26:27], v[160:161] op_sel_hi:[1,0]
	v_pk_mul_f32 v[28:29], v[28:29], v[160:161] op_sel_hi:[1,0]
	v_pk_mul_f32 v[30:31], v[30:31], v[160:161] op_sel_hi:[1,0]
	v_pk_mul_f32 v[32:33], v[32:33], v[160:161] op_sel_hi:[1,0]
	v_pk_mul_f32 v[2:3], v[2:3], v[160:161] op_sel_hi:[1,0]
	v_pk_mul_f32 v[4:5], v[4:5], v[160:161] op_sel_hi:[1,0]
	v_pk_mul_f32 v[6:7], v[6:7], v[160:161] op_sel_hi:[1,0]
	v_pk_mul_f32 v[8:9], v[8:9], v[160:161] op_sel_hi:[1,0]
	v_pk_mul_f32 v[10:11], v[10:11], v[160:161] op_sel_hi:[1,0]
	v_pk_mul_f32 v[12:13], v[12:13], v[160:161] op_sel_hi:[1,0]
	v_pk_mul_f32 v[14:15], v[14:15], v[160:161] op_sel_hi:[1,0]
	v_pk_mul_f32 v[16:17], v[16:17], v[160:161] op_sel_hi:[1,0]
	s_branch .Lm21_pv

; #define LAS __attribute__((address_space(3)))
; template <int MODE  > ...
;     ...
;         if (has_next) {
;             LAS bf16_t* kb = (LAS bf16_t*)(lds + A_KBUF) + (cur ^ 1) * 64 * KPITCH;
;             *(LAS u32x4*)(kb + skey * KPITCH + schunk * 8) = kreg;
;             if (NEEDV) { LAS bf16_t* vb = (LAS bf16_t*)(lds + A_VBUF) + (cur ^ 1) * 64 * VPITCH;
;                 *(LAS u32x4*)(vb + skey * VPITCH + schunk * 8) = vreg; }
;         }
;         __syncthreads();
;         if (!has_next) break;
;         j = jn; cur ^= 1;
.Lm21_w1:
	ds_write_b128 v165, v[130:133]
	ds_write_b128 v166, v[134:137] offset:18432
.Lm2_bot1:
	s_waitcnt lgkmcnt(0)
	s_barrier
	s_cmp_eq_u32 s18, 0
	s_cbranch_scc1 .Lm2_exit
	s_mov_b32 s20, s62
	s_mov_b32 s62, s4
	s_mov_b32 s18, s19
	s_branch .LBB0_268
